# int8 weight-strip converter rewritten (one 16B-load pass, register-resident strip), 3 sites, code phase kept mod 256
# speedup vs baseline: 1.1245x; 1.1245x over previous
; #define TIDX opq((int)threadIdx.x)
; __device__ __forceinline__ void convert_i8_strip(const float* W, int ldw, signed char* WT, float* SWp, float* scr, int rmul, int radd) {
;     const int t = TIDX, kg = t >> 6, nn = t & 63;
;     float am = 0.f;
; #pragma unroll 1
;     for (int i0 = 0; i0 < 128; i0 += 64) {
;         float v[64];
; #pragma unroll
;         for (int i = 0; i < 64; ++i) v[i] = W[(size_t)(kg + 8 * (i0 + i)) * ldw + nn];
; #pragma unroll
;         for (int i = 0; i < 64; ++i) am = fmaxf(am, fabsf(v[i]));
; __device__ __forceinline__ void convert_strip(const Ctx& c, float* scr, int l, int s) {
;     if (s < 64) { const int n = s >> 4, cs = (s & 15) * 64;
;         convert_i8_strip(c.w_gate + (size_t)(l * 4 + n) * DM * DM + cs, DM, c.Wg8 + ((size_t)l * 4096 + n * 1024 + cs) * DM, c.SW + (size_t)l * 4096 + n * 1024 + cs, scr, 1, 0); }
;     else { const int cs = (s - 64) * 64;
;         const int rmul = (cs >= ZB && cs < ZQ) ? 2 : 1, radd = (cs >= ZB && cs < ZB + 256) ? cs - ZB : ((cs >= ZB + 256 && cs < ZQ) ? cs - ZB - 511 : 0);
;         convert_i8_strip(c.w_in + (size_t)l * DM * DIN + cs, DIN, c.Win8 + ((size_t)l * DIN + cs) * DM, c.SWI + (size_t)l * DIN + cs, scr, rmul, radd); }
.LBB0_9:
.Lns_p0:
	s_mov_b32 s60, 0
	s_add_u32 s61, s26, 64
	s_barrier
	v_readlane_b32 s62, v255, 0
	v_readlane_b32 s63, v255, 1
	s_load_dwordx2 s[64:65], s[62:63], 0x10
	s_load_dwordx2 s[66:67], s[62:63], 0x60
	s_load_dwordx2 s[68:69], s[62:63], 0x88
	s_mov_b32 s81, 0
	s_mov_b32 s82, 0
	s_cmp_lt_u32 s61, 64
	s_cbranch_scc0 .Lns_p0_win
	s_lshr_b32 s70, s61, 4
	s_and_b32 s71, s61, 15
	s_lshl_b32 s71, s71, 6
	s_lshl_b32 s72, s60, 2
	s_add_u32 s72, s72, s70
	s_lshl_b32 s73, s72, 10
	s_add_u32 s73, s73, s71
	s_lshl_b32 s74, s72, 22
	s_lshl_b32 s75, s71, 2
	s_add_u32 s74, s74, s75
	s_waitcnt lgkmcnt(0)
	s_add_u32 s76, s66, s74
	s_addc_u32 s77, s67, 0
	s_movk_i32 s78, 0x1000
	s_mov_b32 s79, 0x1110000
	s_mov_b32 s80, 0x1dd28000
	s_branch .Lns_p0_go
.Lns_p0_win:
	s_sub_u32 s71, s61, 64
	s_lshl_b32 s71, s71, 6
	s_mul_i32 s73, s60, 0x1100
	s_add_u32 s73, s73, s71
	s_mul_i32 s74, s60, 0x1100000
	s_lshl_b32 s75, s71, 2
	s_add_u32 s74, s74, s75
	s_waitcnt lgkmcnt(0)
	s_add_u32 s76, s64, s74
	s_addc_u32 s77, s65, 0
	s_movk_i32 s78, 0x4400
	s_mov_b32 s79, 0x890000
	s_mov_b32 s80, 0x1dd30000
	s_cmp_lt_u32 s71, 0x100
	s_cbranch_scc1 .Lns_p0_go
	s_cmp_ge_u32 s71, 0x300
	s_cbranch_scc1 .Lns_p0_go
	s_mov_b32 s81, 1
	s_sub_u32 s82, s71, 0x100
	s_cmp_lt_u32 s71, 0x200
	s_cbranch_scc1 .Lns_p0_go
	s_sub_u32 s82, s71, 0x2ff
.Lns_p0_go:
	s_add_u32 s73, s73, s82
	s_lshl_b32 s74, s73, 10
	s_add_u32 s74, s74, s79
	s_add_u32 s70, s68, s74
	s_addc_u32 s71, s69, 0
	s_lshl_b32 s74, s73, 2
	s_add_u32 s74, s74, s80
	s_add_u32 s72, s68, s74
	s_addc_u32 s73, s69, 0
	v_and_b32_e32 v89, 15, v0
	v_lshrrev_b32_e32 v91, 4, v0
	v_lshlrev_b32_e32 v91, 5, v91
	v_lshlrev_b32_e32 v88, 4, v0
	v_mul_lo_u32 v90, v91, s78
	v_lshl_add_u32 v90, v89, 4, v90
	s_add_u32 s74, s81, 12
	v_lshlrev_b32_e32 v248, s74, v89
	v_add_u32_e32 v248, v248, v91
	s_lshl_b32 s75, 0x400, s81
	v_add_u32_e32 v249, s75, v248
	s_lshl_b32 s75, 0x800, s81
	v_add_u32_e32 v250, s75, v248
	s_lshl_b32 s75, 0xc00, s81
	v_add_u32_e32 v251, s75, v248
	s_add_u32 s82, s76, s78
	s_addc_u32 s83, s77, 0
	global_load_dwordx4 v[96:99], v90, s[76:77]
	s_add_u32 s76, s76, s78
	s_addc_u32 s77, s77, 0
	s_add_u32 s76, s76, s78
	s_addc_u32 s77, s77, 0
	global_load_dwordx4 v[100:103], v90, s[82:83]
	s_add_u32 s82, s82, s78
	s_addc_u32 s83, s83, 0
	s_add_u32 s82, s82, s78
	s_addc_u32 s83, s83, 0
	global_load_dwordx4 v[104:107], v90, s[76:77]
	s_add_u32 s76, s76, s78
	s_addc_u32 s77, s77, 0
	s_add_u32 s76, s76, s78
	s_addc_u32 s77, s77, 0
	global_load_dwordx4 v[108:111], v90, s[82:83]
	s_add_u32 s82, s82, s78
	s_addc_u32 s83, s83, 0
	s_add_u32 s82, s82, s78
	s_addc_u32 s83, s83, 0
	global_load_dwordx4 v[112:115], v90, s[76:77]
	s_add_u32 s76, s76, s78
	s_addc_u32 s77, s77, 0
	s_add_u32 s76, s76, s78
	s_addc_u32 s77, s77, 0
	global_load_dwordx4 v[116:119], v90, s[82:83]
	s_add_u32 s82, s82, s78
	s_addc_u32 s83, s83, 0
	s_add_u32 s82, s82, s78
	s_addc_u32 s83, s83, 0
	global_load_dwordx4 v[120:123], v90, s[76:77]
	s_add_u32 s76, s76, s78
	s_addc_u32 s77, s77, 0
	s_add_u32 s76, s76, s78
	s_addc_u32 s77, s77, 0
	global_load_dwordx4 v[124:127], v90, s[82:83]
	s_add_u32 s82, s82, s78
	s_addc_u32 s83, s83, 0
	s_add_u32 s82, s82, s78
	s_addc_u32 s83, s83, 0
	global_load_dwordx4 v[128:131], v90, s[76:77]
	s_add_u32 s76, s76, s78
	s_addc_u32 s77, s77, 0
	s_add_u32 s76, s76, s78
	s_addc_u32 s77, s77, 0
	global_load_dwordx4 v[132:135], v90, s[82:83]
	s_add_u32 s82, s82, s78
	s_addc_u32 s83, s83, 0
	s_add_u32 s82, s82, s78
	s_addc_u32 s83, s83, 0
	global_load_dwordx4 v[136:139], v90, s[76:77]
	s_add_u32 s76, s76, s78
	s_addc_u32 s77, s77, 0
	s_add_u32 s76, s76, s78
	s_addc_u32 s77, s77, 0
	global_load_dwordx4 v[140:143], v90, s[82:83]
	s_add_u32 s82, s82, s78
	s_addc_u32 s83, s83, 0
	s_add_u32 s82, s82, s78
	s_addc_u32 s83, s83, 0
	global_load_dwordx4 v[144:147], v90, s[76:77]
	s_add_u32 s76, s76, s78
	s_addc_u32 s77, s77, 0
	s_add_u32 s76, s76, s78
	s_addc_u32 s77, s77, 0
	global_load_dwordx4 v[148:151], v90, s[82:83]
	s_add_u32 s82, s82, s78
	s_addc_u32 s83, s83, 0
	s_add_u32 s82, s82, s78
	s_addc_u32 s83, s83, 0
	global_load_dwordx4 v[152:155], v90, s[76:77]
	s_add_u32 s76, s76, s78
	s_addc_u32 s77, s77, 0
	s_add_u32 s76, s76, s78
	s_addc_u32 s77, s77, 0
	global_load_dwordx4 v[156:159], v90, s[82:83]
	s_add_u32 s82, s82, s78
	s_addc_u32 s83, s83, 0
	s_add_u32 s82, s82, s78
	s_addc_u32 s83, s83, 0
	global_load_dwordx4 v[160:163], v90, s[76:77]
	s_add_u32 s76, s76, s78
	s_addc_u32 s77, s77, 0
	s_add_u32 s76, s76, s78
	s_addc_u32 s77, s77, 0
	global_load_dwordx4 v[164:167], v90, s[82:83]
	s_add_u32 s82, s82, s78
	s_addc_u32 s83, s83, 0
	s_add_u32 s82, s82, s78
	s_addc_u32 s83, s83, 0
	global_load_dwordx4 v[168:171], v90, s[76:77]
	s_add_u32 s76, s76, s78
	s_addc_u32 s77, s77, 0
	s_add_u32 s76, s76, s78
	s_addc_u32 s77, s77, 0
	global_load_dwordx4 v[172:175], v90, s[82:83]
	s_add_u32 s82, s82, s78
	s_addc_u32 s83, s83, 0
	s_add_u32 s82, s82, s78
	s_addc_u32 s83, s83, 0
	global_load_dwordx4 v[176:179], v90, s[76:77]
	s_add_u32 s76, s76, s78
	s_addc_u32 s77, s77, 0
	s_add_u32 s76, s76, s78
	s_addc_u32 s77, s77, 0
	global_load_dwordx4 v[180:183], v90, s[82:83]
	s_add_u32 s82, s82, s78
	s_addc_u32 s83, s83, 0
	s_add_u32 s82, s82, s78
	s_addc_u32 s83, s83, 0
	global_load_dwordx4 v[184:187], v90, s[76:77]
	s_add_u32 s76, s76, s78
	s_addc_u32 s77, s77, 0
	s_add_u32 s76, s76, s78
	s_addc_u32 s77, s77, 0
	global_load_dwordx4 v[188:191], v90, s[82:83]
	s_add_u32 s82, s82, s78
	s_addc_u32 s83, s83, 0
	s_add_u32 s82, s82, s78
	s_addc_u32 s83, s83, 0
	global_load_dwordx4 v[192:195], v90, s[76:77]
	s_add_u32 s76, s76, s78
	s_addc_u32 s77, s77, 0
	s_add_u32 s76, s76, s78
	s_addc_u32 s77, s77, 0
	global_load_dwordx4 v[196:199], v90, s[82:83]
	s_add_u32 s82, s82, s78
	s_addc_u32 s83, s83, 0
	s_add_u32 s82, s82, s78
	s_addc_u32 s83, s83, 0
	global_load_dwordx4 v[200:203], v90, s[76:77]
	s_add_u32 s76, s76, s78
	s_addc_u32 s77, s77, 0
	s_add_u32 s76, s76, s78
	s_addc_u32 s77, s77, 0
	global_load_dwordx4 v[204:207], v90, s[82:83]
	s_add_u32 s82, s82, s78
	s_addc_u32 s83, s83, 0
	s_add_u32 s82, s82, s78
	s_addc_u32 s83, s83, 0
	global_load_dwordx4 v[208:211], v90, s[76:77]
	s_add_u32 s76, s76, s78
	s_addc_u32 s77, s77, 0
	s_add_u32 s76, s76, s78
	s_addc_u32 s77, s77, 0
	global_load_dwordx4 v[212:215], v90, s[82:83]
	s_add_u32 s82, s82, s78
	s_addc_u32 s83, s83, 0
	s_add_u32 s82, s82, s78
	s_addc_u32 s83, s83, 0
	global_load_dwordx4 v[216:219], v90, s[76:77]
	global_load_dwordx4 v[220:223], v90, s[82:83]
	v_lshlrev_b32_e32 v89, 4, v89
	s_mov_b32 s98, 0x0c0c0400
	s_waitcnt vmcnt(29)
; __device__ __forceinline__ void convert_i8_strip(const float* W, int ldw, signed char* WT, float* SWp, float* scr, int rmul, int radd) {
;     ...
;         for (int i = 0; i < 64; ++i) am = fmaxf(am, fabsf(v[i]));
;     }
;     scr[kg * 64 + nn] = am;
;     __syncthreads();
;     if (t < 64) { float m = scr[t];
; #pragma unroll
;         for (int k = 1; k < 8; ++k) m = fmaxf(m, scr[k * 64 + t]);
;         scr[512 + t] = m; SWp[rmul * t + radd] = m * (1.f / 127.f); }
;     __syncthreads();
;     const float cm = scr[512 + nn], inv = cm > 0.f ? 127.f / cm : 0.f;
	v_max3_f32 v92, |v96|, |v100|, |v104|
	v_max3_f32 v93, |v97|, |v101|, |v105|
	v_max3_f32 v94, |v98|, |v102|, |v106|
	v_max3_f32 v95, |v99|, |v103|, |v107|
	s_waitcnt vmcnt(27)
	v_max3_f32 v92, v92, |v108|, |v112|
	v_max3_f32 v93, v93, |v109|, |v113|
	v_max3_f32 v94, v94, |v110|, |v114|
	v_max3_f32 v95, v95, |v111|, |v115|
	s_waitcnt vmcnt(25)
	v_max3_f32 v92, v92, |v116|, |v120|
	v_max3_f32 v93, v93, |v117|, |v121|
	v_max3_f32 v94, v94, |v118|, |v122|
	v_max3_f32 v95, v95, |v119|, |v123|
	s_waitcnt vmcnt(23)
	v_max3_f32 v92, v92, |v124|, |v128|
	v_max3_f32 v93, v93, |v125|, |v129|
	v_max3_f32 v94, v94, |v126|, |v130|
	v_max3_f32 v95, v95, |v127|, |v131|
	s_waitcnt vmcnt(21)
	v_max3_f32 v92, v92, |v132|, |v136|
	v_max3_f32 v93, v93, |v133|, |v137|
	v_max3_f32 v94, v94, |v134|, |v138|
	v_max3_f32 v95, v95, |v135|, |v139|
	s_waitcnt vmcnt(19)
	v_max3_f32 v92, v92, |v140|, |v144|
	v_max3_f32 v93, v93, |v141|, |v145|
	v_max3_f32 v94, v94, |v142|, |v146|
	v_max3_f32 v95, v95, |v143|, |v147|
	s_waitcnt vmcnt(17)
	v_max3_f32 v92, v92, |v148|, |v152|
	v_max3_f32 v93, v93, |v149|, |v153|
	v_max3_f32 v94, v94, |v150|, |v154|
	v_max3_f32 v95, v95, |v151|, |v155|
	s_waitcnt vmcnt(15)
	v_max3_f32 v92, v92, |v156|, |v160|
	v_max3_f32 v93, v93, |v157|, |v161|
	v_max3_f32 v94, v94, |v158|, |v162|
	v_max3_f32 v95, v95, |v159|, |v163|
	s_waitcnt vmcnt(13)
	v_max3_f32 v92, v92, |v164|, |v168|
	v_max3_f32 v93, v93, |v165|, |v169|
	v_max3_f32 v94, v94, |v166|, |v170|
	v_max3_f32 v95, v95, |v167|, |v171|
	s_waitcnt vmcnt(11)
	v_max3_f32 v92, v92, |v172|, |v176|
	v_max3_f32 v93, v93, |v173|, |v177|
	v_max3_f32 v94, v94, |v174|, |v178|
	v_max3_f32 v95, v95, |v175|, |v179|
	s_waitcnt vmcnt(9)
	v_max3_f32 v92, v92, |v180|, |v184|
	v_max3_f32 v93, v93, |v181|, |v185|
	v_max3_f32 v94, v94, |v182|, |v186|
	v_max3_f32 v95, v95, |v183|, |v187|
	s_waitcnt vmcnt(7)
	v_max3_f32 v92, v92, |v188|, |v192|
	v_max3_f32 v93, v93, |v189|, |v193|
	v_max3_f32 v94, v94, |v190|, |v194|
	v_max3_f32 v95, v95, |v191|, |v195|
	s_waitcnt vmcnt(5)
	v_max3_f32 v92, v92, |v196|, |v200|
	v_max3_f32 v93, v93, |v197|, |v201|
	v_max3_f32 v94, v94, |v198|, |v202|
	v_max3_f32 v95, v95, |v199|, |v203|
	s_waitcnt vmcnt(3)
	v_max3_f32 v92, v92, |v204|, |v208|
	v_max3_f32 v93, v93, |v205|, |v209|
	v_max3_f32 v94, v94, |v206|, |v210|
	v_max3_f32 v95, v95, |v207|, |v211|
	s_waitcnt vmcnt(1)
	v_max3_f32 v92, v92, |v212|, |v216|
	v_max3_f32 v93, v93, |v213|, |v217|
	v_max3_f32 v94, v94, |v214|, |v218|
	v_max3_f32 v95, v95, |v215|, |v219|
	s_waitcnt vmcnt(0)
	v_max_f32_e64 v92, v92, |v220|
	v_max_f32_e64 v93, v93, |v221|
	v_max_f32_e64 v94, v94, |v222|
	v_max_f32_e64 v95, v95, |v223|
	ds_write_b128 v88, v[92:95]
	s_waitcnt lgkmcnt(0)
	s_barrier
	ds_read_b128 v[224:227], v89 offset:0
	ds_read_b128 v[228:231], v89 offset:256
	ds_read_b128 v[232:235], v89 offset:512
	ds_read_b128 v[236:239], v89 offset:768
	s_waitcnt lgkmcnt(0)
	v_max3_f32 v92, v224, v228, v232
	v_max_f32_e32 v92, v92, v236
	v_max3_f32 v93, v225, v229, v233
	v_max_f32_e32 v93, v93, v237
	v_max3_f32 v94, v226, v230, v234
	v_max_f32_e32 v94, v94, v238
	v_max3_f32 v95, v227, v231, v235
	v_max_f32_e32 v95, v95, v239
	ds_read_b128 v[224:227], v89 offset:1024
	ds_read_b128 v[228:231], v89 offset:1280
	ds_read_b128 v[232:235], v89 offset:1536
	ds_read_b128 v[236:239], v89 offset:1792
	s_waitcnt lgkmcnt(0)
	v_max3_f32 v92, v92, v224, v228
	v_max3_f32 v92, v92, v232, v236
	v_max3_f32 v93, v93, v225, v229
	v_max3_f32 v93, v93, v233, v237
	v_max3_f32 v94, v94, v226, v230
	v_max3_f32 v94, v94, v234, v238
	v_max3_f32 v95, v95, v227, v231
	v_max3_f32 v95, v95, v235, v239
	ds_read_b128 v[224:227], v89 offset:2048
	ds_read_b128 v[228:231], v89 offset:2304
	ds_read_b128 v[232:235], v89 offset:2560
	ds_read_b128 v[236:239], v89 offset:2816
	s_waitcnt lgkmcnt(0)
	v_max3_f32 v92, v92, v224, v228
	v_max3_f32 v92, v92, v232, v236
	v_max3_f32 v93, v93, v225, v229
	v_max3_f32 v93, v93, v233, v237
	v_max3_f32 v94, v94, v226, v230
	v_max3_f32 v94, v94, v234, v238
	v_max3_f32 v95, v95, v227, v231
	v_max3_f32 v95, v95, v235, v239
	ds_read_b128 v[224:227], v89 offset:3072
	ds_read_b128 v[228:231], v89 offset:3328
	ds_read_b128 v[232:235], v89 offset:3584
	ds_read_b128 v[236:239], v89 offset:3840
	s_waitcnt lgkmcnt(0)
	v_max3_f32 v92, v92, v224, v228
	v_max3_f32 v92, v92, v232, v236
	v_max3_f32 v93, v93, v225, v229
	v_max3_f32 v93, v93, v233, v237
	v_max3_f32 v94, v94, v226, v230
	v_max3_f32 v94, v94, v234, v238
	v_max3_f32 v95, v95, v227, v231
	v_max3_f32 v95, v95, v235, v239
	ds_read_b128 v[224:227], v89 offset:4096
	ds_read_b128 v[228:231], v89 offset:4352
	ds_read_b128 v[232:235], v89 offset:4608
	ds_read_b128 v[236:239], v89 offset:4864
	s_waitcnt lgkmcnt(0)
	v_max3_f32 v92, v92, v224, v228
	v_max3_f32 v92, v92, v232, v236
	v_max3_f32 v93, v93, v225, v229
	v_max3_f32 v93, v93, v233, v237
	v_max3_f32 v94, v94, v226, v230
	v_max3_f32 v94, v94, v234, v238
	v_max3_f32 v95, v95, v227, v231
	v_max3_f32 v95, v95, v235, v239
	ds_read_b128 v[224:227], v89 offset:5120
	ds_read_b128 v[228:231], v89 offset:5376
	ds_read_b128 v[232:235], v89 offset:5632
	ds_read_b128 v[236:239], v89 offset:5888
	s_waitcnt lgkmcnt(0)
	v_max3_f32 v92, v92, v224, v228
	v_max3_f32 v92, v92, v232, v236
	v_max3_f32 v93, v93, v225, v229
	v_max3_f32 v93, v93, v233, v237
	v_max3_f32 v94, v94, v226, v230
	v_max3_f32 v94, v94, v234, v238
	v_max3_f32 v95, v95, v227, v231
	v_max3_f32 v95, v95, v235, v239
	ds_read_b128 v[224:227], v89 offset:6144
	ds_read_b128 v[228:231], v89 offset:6400
	ds_read_b128 v[232:235], v89 offset:6656
	ds_read_b128 v[236:239], v89 offset:6912
	s_waitcnt lgkmcnt(0)
	v_max3_f32 v92, v92, v224, v228
	v_max3_f32 v92, v92, v232, v236
	v_max3_f32 v93, v93, v225, v229
	v_max3_f32 v93, v93, v233, v237
	v_max3_f32 v94, v94, v226, v230
	v_max3_f32 v94, v94, v234, v238
	v_max3_f32 v95, v95, v227, v231
	v_max3_f32 v95, v95, v235, v239
	ds_read_b128 v[224:227], v89 offset:7168
	ds_read_b128 v[228:231], v89 offset:7424
	ds_read_b128 v[232:235], v89 offset:7680
	ds_read_b128 v[236:239], v89 offset:7936
	s_waitcnt lgkmcnt(0)
	v_max3_f32 v92, v92, v224, v228
	v_max3_f32 v92, v92, v232, v236
	v_max3_f32 v93, v93, v225, v229
	v_max3_f32 v93, v93, v233, v237
	v_max3_f32 v94, v94, v226, v230
	v_max3_f32 v94, v94, v234, v238
	v_max3_f32 v95, v95, v227, v231
	v_max3_f32 v95, v95, v235, v239
	s_barrier
; __device__ __forceinline__ void convert_i8_strip(const float* W, int ldw, signed char* WT, float* SWp, float* scr, int rmul, int radd) {
;     ...
;     if (t < 64) { float m = scr[t];
; #pragma unroll
;         for (int k = 1; k < 8; ++k) m = fmaxf(m, scr[k * 64 + t]);
;         scr[512 + t] = m; SWp[rmul * t + radd] = m * (1.f / 127.f); }
;     __syncthreads();
;     const float cm = scr[512 + nn], inv = cm > 0.f ? 127.f / cm : 0.f;
;     __syncthreads();
;     float r[8];
; #pragma unroll
;     for (int i = 0; i < 8; ++i) r[i] = W[(size_t)(kg + 8 * i) * ldw + nn];
; #pragma unroll 1
;     for (int kb = 0; kb < 16; ++kb) {
; #pragma unroll
;         for (int i = 0; i < 8; ++i) scr[1024 + (kg + 8 * i) * 65 + nn] = r[i] * inv + 12582912.0f;
;         __syncthreads();
;         if (kb + 1 < 16) {
; #pragma unroll
;             for (int i = 0; i < 8; ++i) r[i] = W[(size_t)((kb + 1) * 64 + kg + 8 * i) * ldw + nn]; }
;         { const int on = t >> 3, kc = t & 7;
;           const unsigned* sp = (const unsigned*)(scr + 1024 + (8 * kc) * 65 + on);
;           u32x2 o; o.x = (sp[0] & 0xffu) | ((sp[65] & 0xffu) << 8) | ((sp[2 * 65] & 0xffu) << 16) | (sp[3 * 65] << 24);
;           o.y = (sp[4 * 65] & 0xffu) | ((sp[5 * 65] & 0xffu) << 8) | ((sp[6 * 65] & 0xffu) << 16) | (sp[7 * 65] << 24);
;           *(u32x2*)(WT + (ptrdiff_t)(rmul * on + radd) * DM + kb * 64 + 8 * kc) = o; }
	s_mov_b32 s99, 0x42fe0000
	s_add_u32 s74, s81, 4
	v_lshrrev_b32_e32 v252, 4, v89
	v_lshlrev_b32_e32 v252, s74, v252
	v_cmp_gt_u32_e32 vcc, 16, v0
	s_and_saveexec_b64 s[100:101], vcc
	v_mul_f32_e32 v224, 0x3c010204, v92
	v_mul_f32_e32 v225, 0x3c010204, v93
	v_mul_f32_e32 v226, 0x3c010204, v94
	v_mul_f32_e32 v227, 0x3c010204, v95
	s_lshl_b32 s75, 0, s81
	v_add_u32_e32 v253, s75, v252
	global_store_dword v253, v224, s[72:73]
	s_lshl_b32 s75, 4, s81
	v_add_u32_e32 v253, s75, v252
	global_store_dword v253, v225, s[72:73]
	s_lshl_b32 s75, 8, s81
	v_add_u32_e32 v253, s75, v252
	global_store_dword v253, v226, s[72:73]
	s_lshl_b32 s75, 12, s81
	v_add_u32_e32 v253, s75, v252
	global_store_dword v253, v227, s[72:73]
	s_mov_b64 exec, s[100:101]
	v_div_scale_f32 v244, s[74:75], v92, v92, s99
	v_rcp_f32_e32 v245, v244
	s_nop 0
	v_fma_f32 v246, -v244, v245, 1.0
	v_fmac_f32_e32 v245, v246, v245
	v_div_scale_f32 v246, vcc, s99, v92, s99
	v_mul_f32_e32 v247, v246, v245
	v_fma_f32 v252, -v244, v247, v246
	v_fmac_f32_e32 v247, v252, v245
	v_fma_f32 v244, -v244, v247, v246
	s_nop 0
	v_div_fmas_f32 v244, v244, v245, v247
	v_div_fixup_f32 v244, v244, v92, s99
	v_cmp_lt_f32_e32 vcc, 0, v92
	s_nop 1
	v_cndmask_b32_e32 v240, 0, v244, vcc
	v_div_scale_f32 v244, s[74:75], v93, v93, s99
	v_rcp_f32_e32 v245, v244
	s_nop 0
	v_fma_f32 v246, -v244, v245, 1.0
	v_fmac_f32_e32 v245, v246, v245
	v_div_scale_f32 v246, vcc, s99, v93, s99
	v_mul_f32_e32 v247, v246, v245
	v_fma_f32 v252, -v244, v247, v246
	v_fmac_f32_e32 v247, v252, v245
	v_fma_f32 v244, -v244, v247, v246
	s_nop 0
	v_div_fmas_f32 v244, v244, v245, v247
	v_div_fixup_f32 v244, v244, v93, s99
	v_cmp_lt_f32_e32 vcc, 0, v93
	s_nop 1
	v_cndmask_b32_e32 v241, 0, v244, vcc
	v_div_scale_f32 v244, s[74:75], v94, v94, s99
	v_rcp_f32_e32 v245, v244
	s_nop 0
	v_fma_f32 v246, -v244, v245, 1.0
	v_fmac_f32_e32 v245, v246, v245
	v_div_scale_f32 v246, vcc, s99, v94, s99
	v_mul_f32_e32 v247, v246, v245
	v_fma_f32 v252, -v244, v247, v246
	v_fmac_f32_e32 v247, v252, v245
	v_fma_f32 v244, -v244, v247, v246
	s_nop 0
	v_div_fmas_f32 v244, v244, v245, v247
	v_div_fixup_f32 v244, v244, v94, s99
	v_cmp_lt_f32_e32 vcc, 0, v94
	s_nop 1
	v_cndmask_b32_e32 v242, 0, v244, vcc
	v_div_scale_f32 v244, s[74:75], v95, v95, s99
	v_rcp_f32_e32 v245, v244
	s_nop 0
	v_fma_f32 v246, -v244, v245, 1.0
	v_fmac_f32_e32 v245, v246, v245
	v_div_scale_f32 v246, vcc, s99, v95, s99
	v_mul_f32_e32 v247, v246, v245
	v_fma_f32 v252, -v244, v247, v246
	v_fmac_f32_e32 v247, v252, v245
	v_fma_f32 v244, -v244, v247, v246
	s_nop 0
	v_div_fmas_f32 v244, v244, v245, v247
	v_div_fixup_f32 v244, v244, v95, s99
	v_cmp_lt_f32_e32 vcc, 0, v95
	s_nop 1
	v_cndmask_b32_e32 v243, 0, v244, vcc
	v_fmaak_f32 v96, v240, v96, 0x4b400000
	v_fmaak_f32 v100, v240, v100, 0x4b400000
	v_fmaak_f32 v104, v240, v104, 0x4b400000
	v_fmaak_f32 v108, v240, v108, 0x4b400000
	v_perm_b32 v252, v100, v96, s98
	v_perm_b32 v253, v108, v104, s98
	v_lshl_or_b32 v224, v253, 16, v252
	v_fmaak_f32 v112, v240, v112, 0x4b400000
	v_fmaak_f32 v116, v240, v116, 0x4b400000
	v_fmaak_f32 v120, v240, v120, 0x4b400000
	v_fmaak_f32 v124, v240, v124, 0x4b400000
	v_perm_b32 v252, v116, v112, s98
	v_perm_b32 v253, v124, v120, s98
	v_lshl_or_b32 v225, v253, 16, v252
	v_fmaak_f32 v128, v240, v128, 0x4b400000
	v_fmaak_f32 v132, v240, v132, 0x4b400000
	v_fmaak_f32 v136, v240, v136, 0x4b400000
	v_fmaak_f32 v140, v240, v140, 0x4b400000
	v_perm_b32 v252, v132, v128, s98
	v_perm_b32 v253, v140, v136, s98
	v_lshl_or_b32 v226, v253, 16, v252
	v_fmaak_f32 v144, v240, v144, 0x4b400000
	v_fmaak_f32 v148, v240, v148, 0x4b400000
	v_fmaak_f32 v152, v240, v152, 0x4b400000
	v_fmaak_f32 v156, v240, v156, 0x4b400000
	v_perm_b32 v252, v148, v144, s98
	v_perm_b32 v253, v156, v152, s98
	v_lshl_or_b32 v227, v253, 16, v252
	global_store_dwordx4 v248, v[224:227], s[70:71] offset:0
	v_fmaak_f32 v97, v241, v97, 0x4b400000
	v_fmaak_f32 v101, v241, v101, 0x4b400000
	v_fmaak_f32 v105, v241, v105, 0x4b400000
	v_fmaak_f32 v109, v241, v109, 0x4b400000
	v_perm_b32 v252, v101, v97, s98
	v_perm_b32 v253, v109, v105, s98
	v_lshl_or_b32 v228, v253, 16, v252
	v_fmaak_f32 v113, v241, v113, 0x4b400000
	v_fmaak_f32 v117, v241, v117, 0x4b400000
	v_fmaak_f32 v121, v241, v121, 0x4b400000
	v_fmaak_f32 v125, v241, v125, 0x4b400000
	v_perm_b32 v252, v117, v113, s98
	v_perm_b32 v253, v125, v121, s98
	v_lshl_or_b32 v229, v253, 16, v252
	v_fmaak_f32 v129, v241, v129, 0x4b400000
	v_fmaak_f32 v133, v241, v133, 0x4b400000
	v_fmaak_f32 v137, v241, v137, 0x4b400000
	v_fmaak_f32 v141, v241, v141, 0x4b400000
	v_perm_b32 v252, v133, v129, s98
	v_perm_b32 v253, v141, v137, s98
	v_lshl_or_b32 v230, v253, 16, v252
	v_fmaak_f32 v145, v241, v145, 0x4b400000
	v_fmaak_f32 v149, v241, v149, 0x4b400000
	v_fmaak_f32 v153, v241, v153, 0x4b400000
	v_fmaak_f32 v157, v241, v157, 0x4b400000
	v_perm_b32 v252, v149, v145, s98
	v_perm_b32 v253, v157, v153, s98
	v_lshl_or_b32 v231, v253, 16, v252
	global_store_dwordx4 v249, v[228:231], s[70:71] offset:0
	v_fmaak_f32 v98, v242, v98, 0x4b400000
	v_fmaak_f32 v102, v242, v102, 0x4b400000
	v_fmaak_f32 v106, v242, v106, 0x4b400000
	v_fmaak_f32 v110, v242, v110, 0x4b400000
	v_perm_b32 v252, v102, v98, s98
	v_perm_b32 v253, v110, v106, s98
	v_lshl_or_b32 v232, v253, 16, v252
	v_fmaak_f32 v114, v242, v114, 0x4b400000
	v_fmaak_f32 v118, v242, v118, 0x4b400000
	v_fmaak_f32 v122, v242, v122, 0x4b400000
	v_fmaak_f32 v126, v242, v126, 0x4b400000
	v_perm_b32 v252, v118, v114, s98
	v_perm_b32 v253, v126, v122, s98
	v_lshl_or_b32 v233, v253, 16, v252
	v_fmaak_f32 v130, v242, v130, 0x4b400000
	v_fmaak_f32 v134, v242, v134, 0x4b400000
	v_fmaak_f32 v138, v242, v138, 0x4b400000
; __device__ __forceinline__ void convert_i8_strip(const float* W, int ldw, signed char* WT, float* SWp, float* scr, int rmul, int radd) {
;     ...
;     for (int kb = 0; kb < 16; ++kb) {
; #pragma unroll
;         for (int i = 0; i < 8; ++i) scr[1024 + (kg + 8 * i) * 65 + nn] = r[i] * inv + 12582912.0f;
;         __syncthreads();
;         if (kb + 1 < 16) {
; #pragma unroll
;             for (int i = 0; i < 8; ++i) r[i] = W[(size_t)((kb + 1) * 64 + kg + 8 * i) * ldw + nn]; }
;         { const int on = t >> 3, kc = t & 7;
;           const unsigned* sp = (const unsigned*)(scr + 1024 + (8 * kc) * 65 + on);
;           u32x2 o; o.x = (sp[0] & 0xffu) | ((sp[65] & 0xffu) << 8) | ((sp[2 * 65] & 0xffu) << 16) | (sp[3 * 65] << 24);
;           o.y = (sp[4 * 65] & 0xffu) | ((sp[5 * 65] & 0xffu) << 8) | ((sp[6 * 65] & 0xffu) << 16) | (sp[7 * 65] << 24);
;           *(u32x2*)(WT + (ptrdiff_t)(rmul * on + radd) * DM + kb * 64 + 8 * kc) = o; }
;         __syncthreads();
	v_fmaak_f32 v142, v242, v142, 0x4b400000
	v_perm_b32 v252, v134, v130, s98
	v_perm_b32 v253, v142, v138, s98
	v_lshl_or_b32 v234, v253, 16, v252
	v_fmaak_f32 v146, v242, v146, 0x4b400000
	v_fmaak_f32 v150, v242, v150, 0x4b400000
	v_fmaak_f32 v154, v242, v154, 0x4b400000
	v_fmaak_f32 v158, v242, v158, 0x4b400000
	v_perm_b32 v252, v150, v146, s98
	v_perm_b32 v253, v158, v154, s98
	v_lshl_or_b32 v235, v253, 16, v252
	global_store_dwordx4 v250, v[232:235], s[70:71] offset:0
	v_fmaak_f32 v99, v243, v99, 0x4b400000
	v_fmaak_f32 v103, v243, v103, 0x4b400000
	v_fmaak_f32 v107, v243, v107, 0x4b400000
	v_fmaak_f32 v111, v243, v111, 0x4b400000
	v_perm_b32 v252, v103, v99, s98
	v_perm_b32 v253, v111, v107, s98
	v_lshl_or_b32 v236, v253, 16, v252
	v_fmaak_f32 v115, v243, v115, 0x4b400000
	v_fmaak_f32 v119, v243, v119, 0x4b400000
	v_fmaak_f32 v123, v243, v123, 0x4b400000
	v_fmaak_f32 v127, v243, v127, 0x4b400000
	v_perm_b32 v252, v119, v115, s98
	v_perm_b32 v253, v127, v123, s98
	v_lshl_or_b32 v237, v253, 16, v252
	v_fmaak_f32 v131, v243, v131, 0x4b400000
	v_fmaak_f32 v135, v243, v135, 0x4b400000
	v_fmaak_f32 v139, v243, v139, 0x4b400000
	v_fmaak_f32 v143, v243, v143, 0x4b400000
	v_perm_b32 v252, v135, v131, s98
	v_perm_b32 v253, v143, v139, s98
	v_lshl_or_b32 v238, v253, 16, v252
	v_fmaak_f32 v147, v243, v147, 0x4b400000
	v_fmaak_f32 v151, v243, v151, 0x4b400000
	v_fmaak_f32 v155, v243, v155, 0x4b400000
	v_fmaak_f32 v159, v243, v159, 0x4b400000
	v_perm_b32 v252, v151, v147, s98
	v_perm_b32 v253, v159, v155, s98
	v_lshl_or_b32 v239, v253, 16, v252
	global_store_dwordx4 v251, v[236:239], s[70:71] offset:0
	s_nop 1
	v_fmaak_f32 v160, v240, v160, 0x4b400000
	v_fmaak_f32 v164, v240, v164, 0x4b400000
	v_fmaak_f32 v168, v240, v168, 0x4b400000
	v_fmaak_f32 v172, v240, v172, 0x4b400000
	v_perm_b32 v252, v164, v160, s98
	v_perm_b32 v253, v172, v168, s98
	v_lshl_or_b32 v224, v253, 16, v252
	v_fmaak_f32 v176, v240, v176, 0x4b400000
	v_fmaak_f32 v180, v240, v180, 0x4b400000
	v_fmaak_f32 v184, v240, v184, 0x4b400000
	v_fmaak_f32 v188, v240, v188, 0x4b400000
	v_perm_b32 v252, v180, v176, s98
	v_perm_b32 v253, v188, v184, s98
	v_lshl_or_b32 v225, v253, 16, v252
	v_fmaak_f32 v192, v240, v192, 0x4b400000
	v_fmaak_f32 v196, v240, v196, 0x4b400000
	v_fmaak_f32 v200, v240, v200, 0x4b400000
	v_fmaak_f32 v204, v240, v204, 0x4b400000
	v_perm_b32 v252, v196, v192, s98
	v_perm_b32 v253, v204, v200, s98
	v_lshl_or_b32 v226, v253, 16, v252
	v_fmaak_f32 v208, v240, v208, 0x4b400000
	v_fmaak_f32 v212, v240, v212, 0x4b400000
	v_fmaak_f32 v216, v240, v216, 0x4b400000
	v_fmaak_f32 v220, v240, v220, 0x4b400000
	v_perm_b32 v252, v212, v208, s98
	v_perm_b32 v253, v220, v216, s98
	v_lshl_or_b32 v227, v253, 16, v252
	global_store_dwordx4 v248, v[224:227], s[70:71] offset:16
	v_fmaak_f32 v161, v241, v161, 0x4b400000
	v_fmaak_f32 v165, v241, v165, 0x4b400000
	v_fmaak_f32 v169, v241, v169, 0x4b400000
	v_fmaak_f32 v173, v241, v173, 0x4b400000
	v_perm_b32 v252, v165, v161, s98
	v_perm_b32 v253, v173, v169, s98
	v_lshl_or_b32 v228, v253, 16, v252
	v_fmaak_f32 v177, v241, v177, 0x4b400000
	v_fmaak_f32 v181, v241, v181, 0x4b400000
	v_fmaak_f32 v185, v241, v185, 0x4b400000
	v_fmaak_f32 v189, v241, v189, 0x4b400000
	v_perm_b32 v252, v181, v177, s98
	v_perm_b32 v253, v189, v185, s98
	v_lshl_or_b32 v229, v253, 16, v252
	v_fmaak_f32 v193, v241, v193, 0x4b400000
	v_fmaak_f32 v197, v241, v197, 0x4b400000
	v_fmaak_f32 v201, v241, v201, 0x4b400000
	v_fmaak_f32 v205, v241, v205, 0x4b400000
	v_perm_b32 v252, v197, v193, s98
	v_perm_b32 v253, v205, v201, s98
	v_lshl_or_b32 v230, v253, 16, v252
	v_fmaak_f32 v209, v241, v209, 0x4b400000
	v_fmaak_f32 v213, v241, v213, 0x4b400000
	v_fmaak_f32 v217, v241, v217, 0x4b400000
	v_fmaak_f32 v221, v241, v221, 0x4b400000
	v_perm_b32 v252, v213, v209, s98
	v_perm_b32 v253, v221, v217, s98
	v_lshl_or_b32 v231, v253, 16, v252
	global_store_dwordx4 v249, v[228:231], s[70:71] offset:16
	v_fmaak_f32 v162, v242, v162, 0x4b400000
	v_fmaak_f32 v166, v242, v166, 0x4b400000
	v_fmaak_f32 v170, v242, v170, 0x4b400000
	v_fmaak_f32 v174, v242, v174, 0x4b400000
	v_perm_b32 v252, v166, v162, s98
	v_perm_b32 v253, v174, v170, s98
	v_lshl_or_b32 v232, v253, 16, v252
	v_fmaak_f32 v178, v242, v178, 0x4b400000
	v_fmaak_f32 v182, v242, v182, 0x4b400000
	v_fmaak_f32 v186, v242, v186, 0x4b400000
	v_fmaak_f32 v190, v242, v190, 0x4b400000
	v_perm_b32 v252, v182, v178, s98
	v_perm_b32 v253, v190, v186, s98
	v_lshl_or_b32 v233, v253, 16, v252
	v_fmaak_f32 v194, v242, v194, 0x4b400000
	v_fmaak_f32 v198, v242, v198, 0x4b400000
	v_fmaak_f32 v202, v242, v202, 0x4b400000
	v_fmaak_f32 v206, v242, v206, 0x4b400000
	v_perm_b32 v252, v198, v194, s98
	v_perm_b32 v253, v206, v202, s98
	v_lshl_or_b32 v234, v253, 16, v252
	v_fmaak_f32 v210, v242, v210, 0x4b400000
	v_fmaak_f32 v214, v242, v214, 0x4b400000
	v_fmaak_f32 v218, v242, v218, 0x4b400000
	v_fmaak_f32 v222, v242, v222, 0x4b400000
	v_perm_b32 v252, v214, v210, s98
	v_perm_b32 v253, v222, v218, s98
	v_lshl_or_b32 v235, v253, 16, v252
	global_store_dwordx4 v250, v[232:235], s[70:71] offset:16
	v_fmaak_f32 v163, v243, v163, 0x4b400000
	v_fmaak_f32 v167, v243, v167, 0x4b400000
	v_fmaak_f32 v171, v243, v171, 0x4b400000
	v_fmaak_f32 v175, v243, v175, 0x4b400000
	v_perm_b32 v252, v167, v163, s98
	v_perm_b32 v253, v175, v171, s98
	v_lshl_or_b32 v236, v253, 16, v252
	v_fmaak_f32 v179, v243, v179, 0x4b400000
	v_fmaak_f32 v183, v243, v183, 0x4b400000
	v_fmaak_f32 v187, v243, v187, 0x4b400000
	v_fmaak_f32 v191, v243, v191, 0x4b400000
	v_perm_b32 v252, v183, v179, s98
	v_perm_b32 v253, v191, v187, s98
	v_lshl_or_b32 v237, v253, 16, v252
	v_fmaak_f32 v195, v243, v195, 0x4b400000
	v_fmaak_f32 v199, v243, v199, 0x4b400000
	v_fmaak_f32 v203, v243, v203, 0x4b400000
	v_fmaak_f32 v207, v243, v207, 0x4b400000
	v_perm_b32 v252, v199, v195, s98
	v_perm_b32 v253, v207, v203, s98
	v_lshl_or_b32 v238, v253, 16, v252
	v_fmaak_f32 v211, v243, v211, 0x4b400000
	v_fmaak_f32 v215, v243, v215, 0x4b400000
	v_fmaak_f32 v219, v243, v219, 0x4b400000
	v_fmaak_f32 v223, v243, v223, 0x4b400000
	v_perm_b32 v252, v215, v211, s98
	v_perm_b32 v253, v223, v219, s98
	v_lshl_or_b32 v239, v253, 16, v252
	global_store_dwordx4 v251, v[236:239], s[70:71] offset:16
	s_branch .LBB0_8
	s_nop 0
	s_nop 0
	s_nop 0
	s_nop 0
	s_nop 0
	s_nop 0
	s_nop 0
	s_nop 0
	s_nop 0
	s_nop 0
	s_nop 0
	s_nop 0
	s_nop 0
	s_nop 0
	s_nop 0
	s_nop 0
	s_nop 0
	s_nop 0
	s_nop 0
	s_nop 0
	s_nop 0
	s_nop 0
	s_nop 0
	s_nop 0
	s_nop 0
	s_nop 0
	s_nop 0
	s_nop 0
	s_nop 0
	s_nop 0
	s_nop 0
	s_nop 0
	s_nop 0
	s_nop 0
	s_nop 0
	s_nop 0
	s_nop 0
	s_nop 0
	s_nop 0
	s_nop 0
	s_nop 0
	s_nop 0
	s_nop 0
	s_nop 0
	s_nop 0
	s_nop 0
	s_nop 0

; __device__ __forceinline__ void convert_strip(const Ctx& c, float* scr, int l, int s) {
;     if (s < 64) { const int n = s >> 4, cs = (s & 15) * 64;
;         convert_i8_strip(c.w_gate + (size_t)(l * 4 + n) * DM * DM + cs, DM, c.Wg8 + ((size_t)l * 4096 + n * 1024 + cs) * DM, c.SW + (size_t)l * 4096 + n * 1024 + cs, scr, 1, 0); }
;     else { const int cs = (s - 64) * 64;
;         const int rmul = (cs >= ZB && cs < ZQ) ? 2 : 1, radd = (cs >= ZB && cs < ZB + 256) ? cs - ZB : ((cs >= ZB + 256 && cs < ZQ) ? cs - ZB - 511 : 0);
;         convert_i8_strip(c.w_in + (size_t)l * DM * DIN + cs, DIN, c.Win8 + ((size_t)l * DIN + cs) * DM, c.SWI + (size_t)l * DIN + cs, scr, rmul, radd); }
; template <int L, int Q>
; __device__ __forceinline__ void layer_phase(unsigned char* lds_raw) {
;     ...
;             if (l < 2 && j_ >= 0) {
;                 for (int s_ = j_; s_ < nstrips; s_ += nidle) { if (s_ < 64) convert_strip(c, (float*)lds_raw, l, s_); else convert_strip(c, (float*)lds_raw, 1, s_); }
.LBB0_212:
.Lns_p1:
	s_cmp_gt_u32 s47, 63
	s_cselect_b32 s60, 1, 0
	s_mov_b32 s61, s47
	s_barrier
	v_readlane_b32 s62, v255, 0
	v_readlane_b32 s63, v255, 1
	s_load_dwordx2 s[64:65], s[62:63], 0x10
	s_load_dwordx2 s[66:67], s[62:63], 0x60
	s_load_dwordx2 s[68:69], s[62:63], 0x88
	s_mov_b32 s81, 0
	s_mov_b32 s82, 0
	s_cmp_lt_u32 s61, 64
	s_cbranch_scc0 .Lns_p1_win
	s_lshr_b32 s70, s61, 4
	s_and_b32 s71, s61, 15
	s_lshl_b32 s71, s71, 6
	s_lshl_b32 s72, s60, 2
	s_add_u32 s72, s72, s70
	s_lshl_b32 s73, s72, 10
	s_add_u32 s73, s73, s71
	s_lshl_b32 s74, s72, 22
	s_lshl_b32 s75, s71, 2
	s_add_u32 s74, s74, s75
	s_waitcnt lgkmcnt(0)
	s_add_u32 s76, s66, s74
	s_addc_u32 s77, s67, 0
	s_movk_i32 s78, 0x1000
	s_mov_b32 s79, 0x1110000
	s_mov_b32 s80, 0x1dd28000
	s_branch .Lns_p1_go

; #define TIDX opq((int)threadIdx.x)
; __device__ __forceinline__ void convert_i8_strip(const float* W, int ldw, signed char* WT, float* SWp, float* scr, int rmul, int radd) {
;     const int t = TIDX, kg = t >> 6, nn = t & 63;
;     float am = 0.f;
; #pragma unroll 1
;     for (int i0 = 0; i0 < 128; i0 += 64) {
;         float v[64];
; #pragma unroll
;         for (int i = 0; i < 64; ++i) v[i] = W[(size_t)(kg + 8 * (i0 + i)) * ldw + nn];
; #pragma unroll
;         for (int i = 0; i < 64; ++i) am = fmaxf(am, fabsf(v[i]));
;     }
.Lns_p1_go:
	s_add_u32 s73, s73, s82
	s_lshl_b32 s74, s73, 10
	s_add_u32 s74, s74, s79
	s_add_u32 s70, s68, s74
	s_addc_u32 s71, s69, 0
	s_lshl_b32 s74, s73, 2
	s_add_u32 s74, s74, s80
	s_add_u32 s72, s68, s74
	s_addc_u32 s73, s69, 0
	v_and_b32_e32 v89, 15, v0
	v_lshrrev_b32_e32 v91, 4, v0
	v_lshlrev_b32_e32 v91, 5, v91
	v_lshlrev_b32_e32 v88, 4, v0
	v_mul_lo_u32 v90, v91, s78
	v_lshl_add_u32 v90, v89, 4, v90
	s_add_u32 s74, s81, 12
	v_lshlrev_b32_e32 v248, s74, v89
	v_add_u32_e32 v248, v248, v91
	s_lshl_b32 s75, 0x400, s81
	v_add_u32_e32 v249, s75, v248
	s_lshl_b32 s75, 0x800, s81
	v_add_u32_e32 v250, s75, v248
	s_lshl_b32 s75, 0xc00, s81
	v_add_u32_e32 v251, s75, v248
	s_add_u32 s82, s76, s78
	s_addc_u32 s83, s77, 0
	global_load_dwordx4 v[96:99], v90, s[76:77]
	s_add_u32 s76, s76, s78
	s_addc_u32 s77, s77, 0
	s_add_u32 s76, s76, s78
	s_addc_u32 s77, s77, 0
	global_load_dwordx4 v[100:103], v90, s[82:83]
	s_add_u32 s82, s82, s78
	s_addc_u32 s83, s83, 0
	s_add_u32 s82, s82, s78
	s_addc_u32 s83, s83, 0
	global_load_dwordx4 v[104:107], v90, s[76:77]
	s_add_u32 s76, s76, s78
	s_addc_u32 s77, s77, 0
	s_add_u32 s76, s76, s78
	s_addc_u32 s77, s77, 0
	global_load_dwordx4 v[108:111], v90, s[82:83]
	s_add_u32 s82, s82, s78
	s_addc_u32 s83, s83, 0
	s_add_u32 s82, s82, s78
	s_addc_u32 s83, s83, 0
	global_load_dwordx4 v[112:115], v90, s[76:77]
	s_add_u32 s76, s76, s78
	s_addc_u32 s77, s77, 0
	s_add_u32 s76, s76, s78
	s_addc_u32 s77, s77, 0
	global_load_dwordx4 v[116:119], v90, s[82:83]
	s_add_u32 s82, s82, s78
	s_addc_u32 s83, s83, 0
	s_add_u32 s82, s82, s78
	s_addc_u32 s83, s83, 0
	global_load_dwordx4 v[120:123], v90, s[76:77]
	s_add_u32 s76, s76, s78
	s_addc_u32 s77, s77, 0
	s_add_u32 s76, s76, s78
	s_addc_u32 s77, s77, 0
	global_load_dwordx4 v[124:127], v90, s[82:83]
	s_add_u32 s82, s82, s78
	s_addc_u32 s83, s83, 0
	s_add_u32 s82, s82, s78
	s_addc_u32 s83, s83, 0
	global_load_dwordx4 v[128:131], v90, s[76:77]
	s_add_u32 s76, s76, s78
	s_addc_u32 s77, s77, 0
	s_add_u32 s76, s76, s78
	s_addc_u32 s77, s77, 0
	global_load_dwordx4 v[132:135], v90, s[82:83]
	s_add_u32 s82, s82, s78
	s_addc_u32 s83, s83, 0
	s_add_u32 s82, s82, s78
	s_addc_u32 s83, s83, 0
	global_load_dwordx4 v[136:139], v90, s[76:77]
	s_add_u32 s76, s76, s78
	s_addc_u32 s77, s77, 0
	s_add_u32 s76, s76, s78
	s_addc_u32 s77, s77, 0
	global_load_dwordx4 v[140:143], v90, s[82:83]
	s_add_u32 s82, s82, s78
	s_addc_u32 s83, s83, 0
	s_add_u32 s82, s82, s78
	s_addc_u32 s83, s83, 0
	global_load_dwordx4 v[144:147], v90, s[76:77]
	s_add_u32 s76, s76, s78
	s_addc_u32 s77, s77, 0
	s_add_u32 s76, s76, s78
	s_addc_u32 s77, s77, 0
	global_load_dwordx4 v[148:151], v90, s[82:83]
	s_add_u32 s82, s82, s78
	s_addc_u32 s83, s83, 0
	s_add_u32 s82, s82, s78
	s_addc_u32 s83, s83, 0
	global_load_dwordx4 v[152:155], v90, s[76:77]
	s_add_u32 s76, s76, s78
	s_addc_u32 s77, s77, 0
	s_add_u32 s76, s76, s78
	s_addc_u32 s77, s77, 0
	global_load_dwordx4 v[156:159], v90, s[82:83]
	s_add_u32 s82, s82, s78
	s_addc_u32 s83, s83, 0
	s_add_u32 s82, s82, s78
	s_addc_u32 s83, s83, 0
	global_load_dwordx4 v[160:163], v90, s[76:77]
	s_add_u32 s76, s76, s78
	s_addc_u32 s77, s77, 0
	s_add_u32 s76, s76, s78
	s_addc_u32 s77, s77, 0
	global_load_dwordx4 v[164:167], v90, s[82:83]
	s_add_u32 s82, s82, s78
	s_addc_u32 s83, s83, 0
	s_add_u32 s82, s82, s78
	s_addc_u32 s83, s83, 0
	global_load_dwordx4 v[168:171], v90, s[76:77]
	s_add_u32 s76, s76, s78
	s_addc_u32 s77, s77, 0
	s_add_u32 s76, s76, s78
	s_addc_u32 s77, s77, 0
	global_load_dwordx4 v[172:175], v90, s[82:83]
	s_add_u32 s82, s82, s78
	s_addc_u32 s83, s83, 0
	s_add_u32 s82, s82, s78
	s_addc_u32 s83, s83, 0
	global_load_dwordx4 v[176:179], v90, s[76:77]
	s_add_u32 s76, s76, s78
	s_addc_u32 s77, s77, 0
	s_add_u32 s76, s76, s78
	s_addc_u32 s77, s77, 0
	global_load_dwordx4 v[180:183], v90, s[82:83]
	s_add_u32 s82, s82, s78
	s_addc_u32 s83, s83, 0
	s_add_u32 s82, s82, s78
	s_addc_u32 s83, s83, 0
	global_load_dwordx4 v[184:187], v90, s[76:77]
	s_add_u32 s76, s76, s78
	s_addc_u32 s77, s77, 0
	s_add_u32 s76, s76, s78
	s_addc_u32 s77, s77, 0
	global_load_dwordx4 v[188:191], v90, s[82:83]
	s_add_u32 s82, s82, s78
	s_addc_u32 s83, s83, 0
	s_add_u32 s82, s82, s78
	s_addc_u32 s83, s83, 0
	global_load_dwordx4 v[192:195], v90, s[76:77]
	s_add_u32 s76, s76, s78
	s_addc_u32 s77, s77, 0
	s_add_u32 s76, s76, s78
	s_addc_u32 s77, s77, 0
	global_load_dwordx4 v[196:199], v90, s[82:83]
	s_add_u32 s82, s82, s78
	s_addc_u32 s83, s83, 0
	s_add_u32 s82, s82, s78
	s_addc_u32 s83, s83, 0
	global_load_dwordx4 v[200:203], v90, s[76:77]
	s_add_u32 s76, s76, s78
	s_addc_u32 s77, s77, 0
	s_add_u32 s76, s76, s78
	s_addc_u32 s77, s77, 0
	global_load_dwordx4 v[204:207], v90, s[82:83]
	s_add_u32 s82, s82, s78
	s_addc_u32 s83, s83, 0
	s_add_u32 s82, s82, s78
	s_addc_u32 s83, s83, 0
	global_load_dwordx4 v[208:211], v90, s[76:77]
	s_add_u32 s76, s76, s78
	s_addc_u32 s77, s77, 0
	s_add_u32 s76, s76, s78
	s_addc_u32 s77, s77, 0
	global_load_dwordx4 v[212:215], v90, s[82:83]
	s_add_u32 s82, s82, s78
	s_addc_u32 s83, s83, 0
	s_add_u32 s82, s82, s78
	s_addc_u32 s83, s83, 0
	global_load_dwordx4 v[216:219], v90, s[76:77]
	global_load_dwordx4 v[220:223], v90, s[82:83]
	v_lshlrev_b32_e32 v89, 4, v89
	s_mov_b32 s98, 0x0c0c0400
	s_waitcnt vmcnt(29)
	v_max3_f32 v92, |v96|, |v100|, |v104|
	v_max3_f32 v93, |v97|, |v101|, |v105|
	v_max3_f32 v94, |v98|, |v102|, |v106|
	v_max3_f32 v95, |v99|, |v103|, |v107|
	s_waitcnt vmcnt(27)
	v_max3_f32 v92, v92, |v108|, |v112|
	v_max3_f32 v93, v93, |v109|, |v113|
	v_max3_f32 v94, v94, |v110|, |v114|
	v_max3_f32 v95, v95, |v111|, |v115|
	s_waitcnt vmcnt(25)
; __device__ __forceinline__ void convert_i8_strip(const float* W, int ldw, signed char* WT, float* SWp, float* scr, int rmul, int radd) {
;     ...
;         for (int i = 0; i < 64; ++i) am = fmaxf(am, fabsf(v[i]));
;     }
;     scr[kg * 64 + nn] = am;
;     __syncthreads();
;     if (t < 64) { float m = scr[t];
; #pragma unroll
;         for (int k = 1; k < 8; ++k) m = fmaxf(m, scr[k * 64 + t]);
;         scr[512 + t] = m; SWp[rmul * t + radd] = m * (1.f / 127.f); }
;     __syncthreads();
;     const float cm = scr[512 + nn], inv = cm > 0.f ? 127.f / cm : 0.f;
	v_max3_f32 v92, v92, |v116|, |v120|
	v_max3_f32 v93, v93, |v117|, |v121|
	v_max3_f32 v94, v94, |v118|, |v122|
	v_max3_f32 v95, v95, |v119|, |v123|
	s_waitcnt vmcnt(23)
	v_max3_f32 v92, v92, |v124|, |v128|
	v_max3_f32 v93, v93, |v125|, |v129|
	v_max3_f32 v94, v94, |v126|, |v130|
	v_max3_f32 v95, v95, |v127|, |v131|
	s_waitcnt vmcnt(21)
	v_max3_f32 v92, v92, |v132|, |v136|
	v_max3_f32 v93, v93, |v133|, |v137|
	v_max3_f32 v94, v94, |v134|, |v138|
	v_max3_f32 v95, v95, |v135|, |v139|
	s_waitcnt vmcnt(19)
	v_max3_f32 v92, v92, |v140|, |v144|
	v_max3_f32 v93, v93, |v141|, |v145|
	v_max3_f32 v94, v94, |v142|, |v146|
	v_max3_f32 v95, v95, |v143|, |v147|
	s_waitcnt vmcnt(17)
	v_max3_f32 v92, v92, |v148|, |v152|
	v_max3_f32 v93, v93, |v149|, |v153|
	v_max3_f32 v94, v94, |v150|, |v154|
	v_max3_f32 v95, v95, |v151|, |v155|
	s_waitcnt vmcnt(15)
	v_max3_f32 v92, v92, |v156|, |v160|
	v_max3_f32 v93, v93, |v157|, |v161|
	v_max3_f32 v94, v94, |v158|, |v162|
	v_max3_f32 v95, v95, |v159|, |v163|
	s_waitcnt vmcnt(13)
	v_max3_f32 v92, v92, |v164|, |v168|
	v_max3_f32 v93, v93, |v165|, |v169|
	v_max3_f32 v94, v94, |v166|, |v170|
	v_max3_f32 v95, v95, |v167|, |v171|
	s_waitcnt vmcnt(11)
	v_max3_f32 v92, v92, |v172|, |v176|
	v_max3_f32 v93, v93, |v173|, |v177|
	v_max3_f32 v94, v94, |v174|, |v178|
	v_max3_f32 v95, v95, |v175|, |v179|
	s_waitcnt vmcnt(9)
	v_max3_f32 v92, v92, |v180|, |v184|
	v_max3_f32 v93, v93, |v181|, |v185|
	v_max3_f32 v94, v94, |v182|, |v186|
	v_max3_f32 v95, v95, |v183|, |v187|
	s_waitcnt vmcnt(7)
	v_max3_f32 v92, v92, |v188|, |v192|
	v_max3_f32 v93, v93, |v189|, |v193|
	v_max3_f32 v94, v94, |v190|, |v194|
	v_max3_f32 v95, v95, |v191|, |v195|
	s_waitcnt vmcnt(5)
	v_max3_f32 v92, v92, |v196|, |v200|
	v_max3_f32 v93, v93, |v197|, |v201|
	v_max3_f32 v94, v94, |v198|, |v202|
	v_max3_f32 v95, v95, |v199|, |v203|
	s_waitcnt vmcnt(3)
	v_max3_f32 v92, v92, |v204|, |v208|
	v_max3_f32 v93, v93, |v205|, |v209|
	v_max3_f32 v94, v94, |v206|, |v210|
	v_max3_f32 v95, v95, |v207|, |v211|
	s_waitcnt vmcnt(1)
	v_max3_f32 v92, v92, |v212|, |v216|
	v_max3_f32 v93, v93, |v213|, |v217|
	v_max3_f32 v94, v94, |v214|, |v218|
	v_max3_f32 v95, v95, |v215|, |v219|
	s_waitcnt vmcnt(0)
	v_max_f32_e64 v92, v92, |v220|
	v_max_f32_e64 v93, v93, |v221|
	v_max_f32_e64 v94, v94, |v222|
	v_max_f32_e64 v95, v95, |v223|
	ds_write_b128 v88, v[92:95]
	s_waitcnt lgkmcnt(0)
	s_barrier
	ds_read_b128 v[224:227], v89 offset:0
	ds_read_b128 v[228:231], v89 offset:256
	ds_read_b128 v[232:235], v89 offset:512
	ds_read_b128 v[236:239], v89 offset:768
	s_waitcnt lgkmcnt(0)
	v_max3_f32 v92, v224, v228, v232
	v_max_f32_e32 v92, v92, v236
	v_max3_f32 v93, v225, v229, v233
	v_max_f32_e32 v93, v93, v237
	v_max3_f32 v94, v226, v230, v234
	v_max_f32_e32 v94, v94, v238
	v_max3_f32 v95, v227, v231, v235
	v_max_f32_e32 v95, v95, v239
	ds_read_b128 v[224:227], v89 offset:1024
	ds_read_b128 v[228:231], v89 offset:1280
	ds_read_b128 v[232:235], v89 offset:1536
	ds_read_b128 v[236:239], v89 offset:1792
	s_waitcnt lgkmcnt(0)
	v_max3_f32 v92, v92, v224, v228
	v_max3_f32 v92, v92, v232, v236
	v_max3_f32 v93, v93, v225, v229
	v_max3_f32 v93, v93, v233, v237
	v_max3_f32 v94, v94, v226, v230
	v_max3_f32 v94, v94, v234, v238
	v_max3_f32 v95, v95, v227, v231
	v_max3_f32 v95, v95, v235, v239
	ds_read_b128 v[224:227], v89 offset:2048
	ds_read_b128 v[228:231], v89 offset:2304
	ds_read_b128 v[232:235], v89 offset:2560
	ds_read_b128 v[236:239], v89 offset:2816
	s_waitcnt lgkmcnt(0)
	v_max3_f32 v92, v92, v224, v228
	v_max3_f32 v92, v92, v232, v236
	v_max3_f32 v93, v93, v225, v229
	v_max3_f32 v93, v93, v233, v237
	v_max3_f32 v94, v94, v226, v230
	v_max3_f32 v94, v94, v234, v238
	v_max3_f32 v95, v95, v227, v231
	v_max3_f32 v95, v95, v235, v239
	ds_read_b128 v[224:227], v89 offset:3072
	ds_read_b128 v[228:231], v89 offset:3328
	ds_read_b128 v[232:235], v89 offset:3584
	ds_read_b128 v[236:239], v89 offset:3840
	s_waitcnt lgkmcnt(0)
	v_max3_f32 v92, v92, v224, v228
	v_max3_f32 v92, v92, v232, v236
	v_max3_f32 v93, v93, v225, v229
	v_max3_f32 v93, v93, v233, v237
	v_max3_f32 v94, v94, v226, v230
	v_max3_f32 v94, v94, v234, v238
	v_max3_f32 v95, v95, v227, v231
	v_max3_f32 v95, v95, v235, v239
	ds_read_b128 v[224:227], v89 offset:4096
	ds_read_b128 v[228:231], v89 offset:4352
	ds_read_b128 v[232:235], v89 offset:4608
	ds_read_b128 v[236:239], v89 offset:4864
	s_waitcnt lgkmcnt(0)
	v_max3_f32 v92, v92, v224, v228
	v_max3_f32 v92, v92, v232, v236
	v_max3_f32 v93, v93, v225, v229
	v_max3_f32 v93, v93, v233, v237
	v_max3_f32 v94, v94, v226, v230
	v_max3_f32 v94, v94, v234, v238
	v_max3_f32 v95, v95, v227, v231
	v_max3_f32 v95, v95, v235, v239
	ds_read_b128 v[224:227], v89 offset:5120
	ds_read_b128 v[228:231], v89 offset:5376
	ds_read_b128 v[232:235], v89 offset:5632
	ds_read_b128 v[236:239], v89 offset:5888
	s_waitcnt lgkmcnt(0)
	v_max3_f32 v92, v92, v224, v228
	v_max3_f32 v92, v92, v232, v236
	v_max3_f32 v93, v93, v225, v229
	v_max3_f32 v93, v93, v233, v237
	v_max3_f32 v94, v94, v226, v230
	v_max3_f32 v94, v94, v234, v238
	v_max3_f32 v95, v95, v227, v231
	v_max3_f32 v95, v95, v235, v239
	ds_read_b128 v[224:227], v89 offset:6144
	ds_read_b128 v[228:231], v89 offset:6400
	ds_read_b128 v[232:235], v89 offset:6656
	ds_read_b128 v[236:239], v89 offset:6912
	s_waitcnt lgkmcnt(0)
	v_max3_f32 v92, v92, v224, v228
	v_max3_f32 v92, v92, v232, v236
	v_max3_f32 v93, v93, v225, v229
	v_max3_f32 v93, v93, v233, v237
	v_max3_f32 v94, v94, v226, v230
	v_max3_f32 v94, v94, v234, v238
	v_max3_f32 v95, v95, v227, v231
	v_max3_f32 v95, v95, v235, v239
	ds_read_b128 v[224:227], v89 offset:7168
	ds_read_b128 v[228:231], v89 offset:7424
	ds_read_b128 v[232:235], v89 offset:7680
	ds_read_b128 v[236:239], v89 offset:7936
	s_waitcnt lgkmcnt(0)
	v_max3_f32 v92, v92, v224, v228
	v_max3_f32 v92, v92, v232, v236
	v_max3_f32 v93, v93, v225, v229
	v_max3_f32 v93, v93, v233, v237
	v_max3_f32 v94, v94, v226, v230
	v_max3_f32 v94, v94, v234, v238
	v_max3_f32 v95, v95, v227, v231
	v_max3_f32 v95, v95, v235, v239
	s_barrier
; __device__ __forceinline__ void convert_i8_strip(const float* W, int ldw, signed char* WT, float* SWp, float* scr, int rmul, int radd) {
;     ...
;     if (t < 64) { float m = scr[t];
; #pragma unroll
;         for (int k = 1; k < 8; ++k) m = fmaxf(m, scr[k * 64 + t]);
;         scr[512 + t] = m; SWp[rmul * t + radd] = m * (1.f / 127.f); }
;     __syncthreads();
;     const float cm = scr[512 + nn], inv = cm > 0.f ? 127.f / cm : 0.f;
;     __syncthreads();
;     float r[8];
; #pragma unroll
;     for (int i = 0; i < 8; ++i) r[i] = W[(size_t)(kg + 8 * i) * ldw + nn];
; #pragma unroll 1
;     for (int kb = 0; kb < 16; ++kb) {
; #pragma unroll
;         for (int i = 0; i < 8; ++i) scr[1024 + (kg + 8 * i) * 65 + nn] = r[i] * inv + 12582912.0f;
;         __syncthreads();
;         if (kb + 1 < 16) {
; #pragma unroll
;             for (int i = 0; i < 8; ++i) r[i] = W[(size_t)((kb + 1) * 64 + kg + 8 * i) * ldw + nn]; }
;         { const int on = t >> 3, kc = t & 7;
;           const unsigned* sp = (const unsigned*)(scr + 1024 + (8 * kc) * 65 + on);
;           u32x2 o; o.x = (sp[0] & 0xffu) | ((sp[65] & 0xffu) << 8) | ((sp[2 * 65] & 0xffu) << 16) | (sp[3 * 65] << 24);
;           o.y = (sp[4 * 65] & 0xffu) | ((sp[5 * 65] & 0xffu) << 8) | ((sp[6 * 65] & 0xffu) << 16) | (sp[7 * 65] << 24);
;           *(u32x2*)(WT + (ptrdiff_t)(rmul * on + radd) * DM + kb * 64 + 8 * kc) = o; }
	s_mov_b32 s99, 0x42fe0000
	s_add_u32 s74, s81, 4
	v_lshrrev_b32_e32 v252, 4, v89
	v_lshlrev_b32_e32 v252, s74, v252
	v_cmp_gt_u32_e32 vcc, 16, v0
	s_and_saveexec_b64 s[100:101], vcc
	v_mul_f32_e32 v224, 0x3c010204, v92
	v_mul_f32_e32 v225, 0x3c010204, v93
	v_mul_f32_e32 v226, 0x3c010204, v94
	v_mul_f32_e32 v227, 0x3c010204, v95
	s_lshl_b32 s75, 0, s81
	v_add_u32_e32 v253, s75, v252
	global_store_dword v253, v224, s[72:73]
	s_lshl_b32 s75, 4, s81
	v_add_u32_e32 v253, s75, v252
	global_store_dword v253, v225, s[72:73]
	s_lshl_b32 s75, 8, s81
	v_add_u32_e32 v253, s75, v252
	global_store_dword v253, v226, s[72:73]
	s_lshl_b32 s75, 12, s81
	v_add_u32_e32 v253, s75, v252
	global_store_dword v253, v227, s[72:73]
	s_mov_b64 exec, s[100:101]
	v_div_scale_f32 v244, s[74:75], v92, v92, s99
	v_rcp_f32_e32 v245, v244
	s_nop 0
	v_fma_f32 v246, -v244, v245, 1.0
	v_fmac_f32_e32 v245, v246, v245
	v_div_scale_f32 v246, vcc, s99, v92, s99
	v_mul_f32_e32 v247, v246, v245
	v_fma_f32 v252, -v244, v247, v246
	v_fmac_f32_e32 v247, v252, v245
	v_fma_f32 v244, -v244, v247, v246
	s_nop 0
	v_div_fmas_f32 v244, v244, v245, v247
	v_div_fixup_f32 v244, v244, v92, s99
	v_cmp_lt_f32_e32 vcc, 0, v92
	s_nop 1
	v_cndmask_b32_e32 v240, 0, v244, vcc
	v_div_scale_f32 v244, s[74:75], v93, v93, s99
	v_rcp_f32_e32 v245, v244
	s_nop 0
	v_fma_f32 v246, -v244, v245, 1.0
	v_fmac_f32_e32 v245, v246, v245
	v_div_scale_f32 v246, vcc, s99, v93, s99
	v_mul_f32_e32 v247, v246, v245
	v_fma_f32 v252, -v244, v247, v246
	v_fmac_f32_e32 v247, v252, v245
	v_fma_f32 v244, -v244, v247, v246
	s_nop 0
	v_div_fmas_f32 v244, v244, v245, v247
	v_div_fixup_f32 v244, v244, v93, s99
	v_cmp_lt_f32_e32 vcc, 0, v93
	s_nop 1
	v_cndmask_b32_e32 v241, 0, v244, vcc
	v_div_scale_f32 v244, s[74:75], v94, v94, s99
	v_rcp_f32_e32 v245, v244
	s_nop 0
	v_fma_f32 v246, -v244, v245, 1.0
	v_fmac_f32_e32 v245, v246, v245
	v_div_scale_f32 v246, vcc, s99, v94, s99
	v_mul_f32_e32 v247, v246, v245
	v_fma_f32 v252, -v244, v247, v246
	v_fmac_f32_e32 v247, v252, v245
	v_fma_f32 v244, -v244, v247, v246
	s_nop 0
	v_div_fmas_f32 v244, v244, v245, v247
	v_div_fixup_f32 v244, v244, v94, s99
	v_cmp_lt_f32_e32 vcc, 0, v94
	s_nop 1
	v_cndmask_b32_e32 v242, 0, v244, vcc
	v_div_scale_f32 v244, s[74:75], v95, v95, s99
	v_rcp_f32_e32 v245, v244
	s_nop 0
	v_fma_f32 v246, -v244, v245, 1.0
	v_fmac_f32_e32 v245, v246, v245
	v_div_scale_f32 v246, vcc, s99, v95, s99
	v_mul_f32_e32 v247, v246, v245
	v_fma_f32 v252, -v244, v247, v246
	v_fmac_f32_e32 v247, v252, v245
	v_fma_f32 v244, -v244, v247, v246
	s_nop 0
	v_div_fmas_f32 v244, v244, v245, v247
	v_div_fixup_f32 v244, v244, v95, s99
	v_cmp_lt_f32_e32 vcc, 0, v95
	s_nop 1
	v_cndmask_b32_e32 v243, 0, v244, vcc
	v_fmaak_f32 v96, v240, v96, 0x4b400000
	v_fmaak_f32 v100, v240, v100, 0x4b400000
	v_fmaak_f32 v104, v240, v104, 0x4b400000
	v_fmaak_f32 v108, v240, v108, 0x4b400000
	v_perm_b32 v252, v100, v96, s98
	v_perm_b32 v253, v108, v104, s98
	v_lshl_or_b32 v224, v253, 16, v252
	v_fmaak_f32 v112, v240, v112, 0x4b400000
	v_fmaak_f32 v116, v240, v116, 0x4b400000
	v_fmaak_f32 v120, v240, v120, 0x4b400000
	v_fmaak_f32 v124, v240, v124, 0x4b400000
	v_perm_b32 v252, v116, v112, s98
	v_perm_b32 v253, v124, v120, s98
	v_lshl_or_b32 v225, v253, 16, v252
	v_fmaak_f32 v128, v240, v128, 0x4b400000
	v_fmaak_f32 v132, v240, v132, 0x4b400000
	v_fmaak_f32 v136, v240, v136, 0x4b400000
	v_fmaak_f32 v140, v240, v140, 0x4b400000
	v_perm_b32 v252, v132, v128, s98
	v_perm_b32 v253, v140, v136, s98
	v_lshl_or_b32 v226, v253, 16, v252
	v_fmaak_f32 v144, v240, v144, 0x4b400000
	v_fmaak_f32 v148, v240, v148, 0x4b400000
	v_fmaak_f32 v152, v240, v152, 0x4b400000
	v_fmaak_f32 v156, v240, v156, 0x4b400000
	v_perm_b32 v252, v148, v144, s98
	v_perm_b32 v253, v156, v152, s98
	v_lshl_or_b32 v227, v253, 16, v252
	global_store_dwordx4 v248, v[224:227], s[70:71] offset:0
	v_fmaak_f32 v97, v241, v97, 0x4b400000
	v_fmaak_f32 v101, v241, v101, 0x4b400000
	v_fmaak_f32 v105, v241, v105, 0x4b400000
	v_fmaak_f32 v109, v241, v109, 0x4b400000
	v_perm_b32 v252, v101, v97, s98
	v_perm_b32 v253, v109, v105, s98
	v_lshl_or_b32 v228, v253, 16, v252
	v_fmaak_f32 v113, v241, v113, 0x4b400000
	v_fmaak_f32 v117, v241, v117, 0x4b400000
	v_fmaak_f32 v121, v241, v121, 0x4b400000
	v_fmaak_f32 v125, v241, v125, 0x4b400000
	v_perm_b32 v252, v117, v113, s98
	v_perm_b32 v253, v125, v121, s98
	v_lshl_or_b32 v229, v253, 16, v252
	v_fmaak_f32 v129, v241, v129, 0x4b400000
	v_fmaak_f32 v133, v241, v133, 0x4b400000
	v_fmaak_f32 v137, v241, v137, 0x4b400000
	v_fmaak_f32 v141, v241, v141, 0x4b400000
	v_perm_b32 v252, v133, v129, s98
	v_perm_b32 v253, v141, v137, s98
	v_lshl_or_b32 v230, v253, 16, v252
	v_fmaak_f32 v145, v241, v145, 0x4b400000
	v_fmaak_f32 v149, v241, v149, 0x4b400000
	v_fmaak_f32 v153, v241, v153, 0x4b400000
	v_fmaak_f32 v157, v241, v157, 0x4b400000
	v_perm_b32 v252, v149, v145, s98
	v_perm_b32 v253, v157, v153, s98
	v_lshl_or_b32 v231, v253, 16, v252
	global_store_dwordx4 v249, v[228:231], s[70:71] offset:0
	v_fmaak_f32 v98, v242, v98, 0x4b400000
	v_fmaak_f32 v102, v242, v102, 0x4b400000
	v_fmaak_f32 v106, v242, v106, 0x4b400000
	v_fmaak_f32 v110, v242, v110, 0x4b400000
	v_perm_b32 v252, v102, v98, s98
	v_perm_b32 v253, v110, v106, s98
	v_lshl_or_b32 v232, v253, 16, v252
	v_fmaak_f32 v114, v242, v114, 0x4b400000
	v_fmaak_f32 v118, v242, v118, 0x4b400000
	v_fmaak_f32 v122, v242, v122, 0x4b400000
	v_fmaak_f32 v126, v242, v126, 0x4b400000
	v_perm_b32 v252, v118, v114, s98
	v_perm_b32 v253, v126, v122, s98
	v_lshl_or_b32 v233, v253, 16, v252
	v_fmaak_f32 v130, v242, v130, 0x4b400000
	v_fmaak_f32 v134, v242, v134, 0x4b400000
	v_fmaak_f32 v138, v242, v138, 0x4b400000
; __device__ __forceinline__ void convert_i8_strip(const float* W, int ldw, signed char* WT, float* SWp, float* scr, int rmul, int radd) {
;     ...
;     for (int kb = 0; kb < 16; ++kb) {
; #pragma unroll
;         for (int i = 0; i < 8; ++i) scr[1024 + (kg + 8 * i) * 65 + nn] = r[i] * inv + 12582912.0f;
;         __syncthreads();
;         if (kb + 1 < 16) {
; #pragma unroll
;             for (int i = 0; i < 8; ++i) r[i] = W[(size_t)((kb + 1) * 64 + kg + 8 * i) * ldw + nn]; }
;         { const int on = t >> 3, kc = t & 7;
;           const unsigned* sp = (const unsigned*)(scr + 1024 + (8 * kc) * 65 + on);
;           u32x2 o; o.x = (sp[0] & 0xffu) | ((sp[65] & 0xffu) << 8) | ((sp[2 * 65] & 0xffu) << 16) | (sp[3 * 65] << 24);
;           o.y = (sp[4 * 65] & 0xffu) | ((sp[5 * 65] & 0xffu) << 8) | ((sp[6 * 65] & 0xffu) << 16) | (sp[7 * 65] << 24);
;           *(u32x2*)(WT + (ptrdiff_t)(rmul * on + radd) * DM + kb * 64 + 8 * kc) = o; }
;         __syncthreads();
	v_fmaak_f32 v142, v242, v142, 0x4b400000
	v_perm_b32 v252, v134, v130, s98
	v_perm_b32 v253, v142, v138, s98
	v_lshl_or_b32 v234, v253, 16, v252
	v_fmaak_f32 v146, v242, v146, 0x4b400000
	v_fmaak_f32 v150, v242, v150, 0x4b400000
	v_fmaak_f32 v154, v242, v154, 0x4b400000
	v_fmaak_f32 v158, v242, v158, 0x4b400000
	v_perm_b32 v252, v150, v146, s98
	v_perm_b32 v253, v158, v154, s98
	v_lshl_or_b32 v235, v253, 16, v252
	global_store_dwordx4 v250, v[232:235], s[70:71] offset:0
	v_fmaak_f32 v99, v243, v99, 0x4b400000
	v_fmaak_f32 v103, v243, v103, 0x4b400000
	v_fmaak_f32 v107, v243, v107, 0x4b400000
	v_fmaak_f32 v111, v243, v111, 0x4b400000
	v_perm_b32 v252, v103, v99, s98
	v_perm_b32 v253, v111, v107, s98
	v_lshl_or_b32 v236, v253, 16, v252
	v_fmaak_f32 v115, v243, v115, 0x4b400000
	v_fmaak_f32 v119, v243, v119, 0x4b400000
	v_fmaak_f32 v123, v243, v123, 0x4b400000
	v_fmaak_f32 v127, v243, v127, 0x4b400000
	v_perm_b32 v252, v119, v115, s98
	v_perm_b32 v253, v127, v123, s98
	v_lshl_or_b32 v237, v253, 16, v252
	v_fmaak_f32 v131, v243, v131, 0x4b400000
	v_fmaak_f32 v135, v243, v135, 0x4b400000
	v_fmaak_f32 v139, v243, v139, 0x4b400000
	v_fmaak_f32 v143, v243, v143, 0x4b400000
	v_perm_b32 v252, v135, v131, s98
	v_perm_b32 v253, v143, v139, s98
	v_lshl_or_b32 v238, v253, 16, v252
	v_fmaak_f32 v147, v243, v147, 0x4b400000
	v_fmaak_f32 v151, v243, v151, 0x4b400000
	v_fmaak_f32 v155, v243, v155, 0x4b400000
	v_fmaak_f32 v159, v243, v159, 0x4b400000
	v_perm_b32 v252, v151, v147, s98
	v_perm_b32 v253, v159, v155, s98
	v_lshl_or_b32 v239, v253, 16, v252
	global_store_dwordx4 v251, v[236:239], s[70:71] offset:0
	s_nop 1
	v_fmaak_f32 v160, v240, v160, 0x4b400000
	v_fmaak_f32 v164, v240, v164, 0x4b400000
	v_fmaak_f32 v168, v240, v168, 0x4b400000
	v_fmaak_f32 v172, v240, v172, 0x4b400000
	v_perm_b32 v252, v164, v160, s98
	v_perm_b32 v253, v172, v168, s98
	v_lshl_or_b32 v224, v253, 16, v252
	v_fmaak_f32 v176, v240, v176, 0x4b400000
	v_fmaak_f32 v180, v240, v180, 0x4b400000
	v_fmaak_f32 v184, v240, v184, 0x4b400000
	v_fmaak_f32 v188, v240, v188, 0x4b400000
	v_perm_b32 v252, v180, v176, s98
	v_perm_b32 v253, v188, v184, s98
	v_lshl_or_b32 v225, v253, 16, v252
	v_fmaak_f32 v192, v240, v192, 0x4b400000
	v_fmaak_f32 v196, v240, v196, 0x4b400000
	v_fmaak_f32 v200, v240, v200, 0x4b400000
	v_fmaak_f32 v204, v240, v204, 0x4b400000
	v_perm_b32 v252, v196, v192, s98
	v_perm_b32 v253, v204, v200, s98
	v_lshl_or_b32 v226, v253, 16, v252
	v_fmaak_f32 v208, v240, v208, 0x4b400000
	v_fmaak_f32 v212, v240, v212, 0x4b400000
	v_fmaak_f32 v216, v240, v216, 0x4b400000
	v_fmaak_f32 v220, v240, v220, 0x4b400000
	v_perm_b32 v252, v212, v208, s98
	v_perm_b32 v253, v220, v216, s98
	v_lshl_or_b32 v227, v253, 16, v252
	global_store_dwordx4 v248, v[224:227], s[70:71] offset:16
	v_fmaak_f32 v161, v241, v161, 0x4b400000
	v_fmaak_f32 v165, v241, v165, 0x4b400000
	v_fmaak_f32 v169, v241, v169, 0x4b400000
	v_fmaak_f32 v173, v241, v173, 0x4b400000
	v_perm_b32 v252, v165, v161, s98
	v_perm_b32 v253, v173, v169, s98
	v_lshl_or_b32 v228, v253, 16, v252
	v_fmaak_f32 v177, v241, v177, 0x4b400000
	v_fmaak_f32 v181, v241, v181, 0x4b400000
	v_fmaak_f32 v185, v241, v185, 0x4b400000
	v_fmaak_f32 v189, v241, v189, 0x4b400000
	v_perm_b32 v252, v181, v177, s98
	v_perm_b32 v253, v189, v185, s98
	v_lshl_or_b32 v229, v253, 16, v252
	v_fmaak_f32 v193, v241, v193, 0x4b400000
	v_fmaak_f32 v197, v241, v197, 0x4b400000
	v_fmaak_f32 v201, v241, v201, 0x4b400000
	v_fmaak_f32 v205, v241, v205, 0x4b400000
	v_perm_b32 v252, v197, v193, s98
	v_perm_b32 v253, v205, v201, s98
	v_lshl_or_b32 v230, v253, 16, v252
	v_fmaak_f32 v209, v241, v209, 0x4b400000
	v_fmaak_f32 v213, v241, v213, 0x4b400000
	v_fmaak_f32 v217, v241, v217, 0x4b400000
	v_fmaak_f32 v221, v241, v221, 0x4b400000
	v_perm_b32 v252, v213, v209, s98
	v_perm_b32 v253, v221, v217, s98
	v_lshl_or_b32 v231, v253, 16, v252
	global_store_dwordx4 v249, v[228:231], s[70:71] offset:16
	v_fmaak_f32 v162, v242, v162, 0x4b400000
	v_fmaak_f32 v166, v242, v166, 0x4b400000
	v_fmaak_f32 v170, v242, v170, 0x4b400000
	v_fmaak_f32 v174, v242, v174, 0x4b400000
	v_perm_b32 v252, v166, v162, s98
	v_perm_b32 v253, v174, v170, s98
	v_lshl_or_b32 v232, v253, 16, v252
	v_fmaak_f32 v178, v242, v178, 0x4b400000
	v_fmaak_f32 v182, v242, v182, 0x4b400000
	v_fmaak_f32 v186, v242, v186, 0x4b400000
	v_fmaak_f32 v190, v242, v190, 0x4b400000
	v_perm_b32 v252, v182, v178, s98
	v_perm_b32 v253, v190, v186, s98
	v_lshl_or_b32 v233, v253, 16, v252
	v_fmaak_f32 v194, v242, v194, 0x4b400000
	v_fmaak_f32 v198, v242, v198, 0x4b400000
	v_fmaak_f32 v202, v242, v202, 0x4b400000
	v_fmaak_f32 v206, v242, v206, 0x4b400000
	v_perm_b32 v252, v198, v194, s98
	v_perm_b32 v253, v206, v202, s98
	v_lshl_or_b32 v234, v253, 16, v252
	v_fmaak_f32 v210, v242, v210, 0x4b400000
	v_fmaak_f32 v214, v242, v214, 0x4b400000
	v_fmaak_f32 v218, v242, v218, 0x4b400000
	v_fmaak_f32 v222, v242, v222, 0x4b400000
	v_perm_b32 v252, v214, v210, s98
	v_perm_b32 v253, v222, v218, s98
	v_lshl_or_b32 v235, v253, 16, v252
	global_store_dwordx4 v250, v[232:235], s[70:71] offset:16
	v_fmaak_f32 v163, v243, v163, 0x4b400000
	v_fmaak_f32 v167, v243, v167, 0x4b400000
	v_fmaak_f32 v171, v243, v171, 0x4b400000
	v_fmaak_f32 v175, v243, v175, 0x4b400000
	v_perm_b32 v252, v167, v163, s98
	v_perm_b32 v253, v175, v171, s98
	v_lshl_or_b32 v236, v253, 16, v252
	v_fmaak_f32 v179, v243, v179, 0x4b400000
	v_fmaak_f32 v183, v243, v183, 0x4b400000
	v_fmaak_f32 v187, v243, v187, 0x4b400000
	v_fmaak_f32 v191, v243, v191, 0x4b400000
	v_perm_b32 v252, v183, v179, s98
	v_perm_b32 v253, v191, v187, s98
	v_lshl_or_b32 v237, v253, 16, v252
	v_fmaak_f32 v195, v243, v195, 0x4b400000
	v_fmaak_f32 v199, v243, v199, 0x4b400000
	v_fmaak_f32 v203, v243, v203, 0x4b400000
	v_fmaak_f32 v207, v243, v207, 0x4b400000
	v_perm_b32 v252, v199, v195, s98
	v_perm_b32 v253, v207, v203, s98
	v_lshl_or_b32 v238, v253, 16, v252
	v_fmaak_f32 v211, v243, v211, 0x4b400000
	v_fmaak_f32 v215, v243, v215, 0x4b400000
	v_fmaak_f32 v219, v243, v219, 0x4b400000
	v_fmaak_f32 v223, v243, v223, 0x4b400000
	v_perm_b32 v252, v215, v211, s98
	v_perm_b32 v253, v223, v219, s98
	v_lshl_or_b32 v239, v253, 16, v252
	global_store_dwordx4 v251, v[236:239], s[70:71] offset:16
	s_branch .LBB0_211
	s_nop 0
	s_nop 0
	s_nop 0
	s_nop 0
	s_nop 0
	s_nop 0
	s_nop 0
	s_nop 0
	s_nop 0
	s_nop 0
	s_nop 0
	s_nop 0
	s_nop 0
	s_nop 0
	s_nop 0
	s_nop 0
	s_nop 0
	s_nop 0
	s_nop 0
	s_nop 0
	s_nop 0
	s_nop 0
	s_nop 0
	s_nop 0
	s_nop 0
	s_nop 0
	s_nop 0
	s_nop 0
	s_nop 0
	s_nop 0
	s_nop 0
	s_nop 0
	s_nop 0
	s_nop 0
	s_nop 0
	s_nop 0
	s_nop 0
	s_nop 0
	s_nop 0
	s_nop 0
	s_nop 0
	s_nop 0
	s_nop 0
	s_nop 0
	s_nop 0
	s_nop 0
	s_nop 0
	s_nop 0
	s_nop 0
	s_nop 0
	s_nop 0
	s_nop 0
	s_nop 0
	s_nop 0
	s_nop 0
	s_nop 0

; __device__ __forceinline__ void convert_strip(const Ctx& c, float* scr, int l, int s) {
;     if (s < 64) { const int n = s >> 4, cs = (s & 15) * 64;
;         convert_i8_strip(c.w_gate + (size_t)(l * 4 + n) * DM * DM + cs, DM, c.Wg8 + ((size_t)l * 4096 + n * 1024 + cs) * DM, c.SW + (size_t)l * 4096 + n * 1024 + cs, scr, 1, 0); }
; template <int L, int Q>
; __device__ __forceinline__ void layer_phase(unsigned char* lds_raw) {
;     ...
;             if (l < 2 && j_ >= 0) {
;                 for (int s_ = j_; s_ < nstrips; s_ += nidle) { if (s_ < 64) convert_strip(c, (float*)lds_raw, l, s_); else convert_strip(c, (float*)lds_raw, 1, s_); }
.LBB0_1585:
.Lns_p6:
	s_mov_b32 s60, 1
	s_mov_b32 s61, s38
	s_barrier
	v_readlane_b32 s62, v255, 0
	v_readlane_b32 s63, v255, 1
	s_load_dwordx2 s[64:65], s[62:63], 0x10
	s_load_dwordx2 s[66:67], s[62:63], 0x60
	s_load_dwordx2 s[68:69], s[62:63], 0x88
	s_mov_b32 s81, 0
	s_mov_b32 s82, 0
	s_cmp_lt_u32 s61, 64
	s_cbranch_scc0 .Lns_p6_win
	s_lshr_b32 s70, s61, 4
	s_and_b32 s71, s61, 15
	s_lshl_b32 s71, s71, 6
	s_lshl_b32 s72, s60, 2
	s_add_u32 s72, s72, s70
	s_lshl_b32 s73, s72, 10
	s_add_u32 s73, s73, s71
	s_lshl_b32 s74, s72, 22
	s_lshl_b32 s75, s71, 2
	s_add_u32 s74, s74, s75
	s_waitcnt lgkmcnt(0)
	s_add_u32 s76, s66, s74
	s_addc_u32 s77, s67, 0
	s_movk_i32 s78, 0x1000
	s_mov_b32 s79, 0x1110000
	s_mov_b32 s80, 0x1dd28000
	s_branch .Lns_p6_go

; #define TIDX opq((int)threadIdx.x)
; __device__ __forceinline__ void convert_i8_strip(const float* W, int ldw, signed char* WT, float* SWp, float* scr, int rmul, int radd) {
;     const int t = TIDX, kg = t >> 6, nn = t & 63;
;     float am = 0.f;
; #pragma unroll 1
;     for (int i0 = 0; i0 < 128; i0 += 64) {
;         float v[64];
; #pragma unroll
;         for (int i = 0; i < 64; ++i) v[i] = W[(size_t)(kg + 8 * (i0 + i)) * ldw + nn];
; #pragma unroll
;         for (int i = 0; i < 64; ++i) am = fmaxf(am, fabsf(v[i]));
;     }
.Lns_p6_go:
	s_add_u32 s73, s73, s82
	s_lshl_b32 s74, s73, 10
	s_add_u32 s74, s74, s79
	s_add_u32 s70, s68, s74
	s_addc_u32 s71, s69, 0
	s_lshl_b32 s74, s73, 2
	s_add_u32 s74, s74, s80
	s_add_u32 s72, s68, s74
	s_addc_u32 s73, s69, 0
	v_and_b32_e32 v89, 15, v0
	v_lshrrev_b32_e32 v91, 4, v0
	v_lshlrev_b32_e32 v91, 5, v91
	v_lshlrev_b32_e32 v88, 4, v0
	v_mul_lo_u32 v90, v91, s78
	v_lshl_add_u32 v90, v89, 4, v90
	s_add_u32 s74, s81, 12
	v_lshlrev_b32_e32 v248, s74, v89
	v_add_u32_e32 v248, v248, v91
	s_lshl_b32 s75, 0x400, s81
	v_add_u32_e32 v249, s75, v248
	s_lshl_b32 s75, 0x800, s81
	v_add_u32_e32 v250, s75, v248
	s_lshl_b32 s75, 0xc00, s81
	v_add_u32_e32 v251, s75, v248
	s_add_u32 s82, s76, s78
	s_addc_u32 s83, s77, 0
	global_load_dwordx4 v[96:99], v90, s[76:77]
	s_add_u32 s76, s76, s78
	s_addc_u32 s77, s77, 0
	s_add_u32 s76, s76, s78
	s_addc_u32 s77, s77, 0
	global_load_dwordx4 v[100:103], v90, s[82:83]
	s_add_u32 s82, s82, s78
	s_addc_u32 s83, s83, 0
	s_add_u32 s82, s82, s78
	s_addc_u32 s83, s83, 0
	global_load_dwordx4 v[104:107], v90, s[76:77]
	s_add_u32 s76, s76, s78
	s_addc_u32 s77, s77, 0
	s_add_u32 s76, s76, s78
	s_addc_u32 s77, s77, 0
	global_load_dwordx4 v[108:111], v90, s[82:83]
	s_add_u32 s82, s82, s78
	s_addc_u32 s83, s83, 0
	s_add_u32 s82, s82, s78
	s_addc_u32 s83, s83, 0
	global_load_dwordx4 v[112:115], v90, s[76:77]
	s_add_u32 s76, s76, s78
	s_addc_u32 s77, s77, 0
	s_add_u32 s76, s76, s78
	s_addc_u32 s77, s77, 0
	global_load_dwordx4 v[116:119], v90, s[82:83]
	s_add_u32 s82, s82, s78
	s_addc_u32 s83, s83, 0
	s_add_u32 s82, s82, s78
	s_addc_u32 s83, s83, 0
	global_load_dwordx4 v[120:123], v90, s[76:77]
	s_add_u32 s76, s76, s78
	s_addc_u32 s77, s77, 0
	s_add_u32 s76, s76, s78
	s_addc_u32 s77, s77, 0
	global_load_dwordx4 v[124:127], v90, s[82:83]
	s_add_u32 s82, s82, s78
	s_addc_u32 s83, s83, 0
	s_add_u32 s82, s82, s78
	s_addc_u32 s83, s83, 0
	global_load_dwordx4 v[128:131], v90, s[76:77]
	s_add_u32 s76, s76, s78
	s_addc_u32 s77, s77, 0
	s_add_u32 s76, s76, s78
	s_addc_u32 s77, s77, 0
	global_load_dwordx4 v[132:135], v90, s[82:83]
	s_add_u32 s82, s82, s78
	s_addc_u32 s83, s83, 0
	s_add_u32 s82, s82, s78
	s_addc_u32 s83, s83, 0
	global_load_dwordx4 v[136:139], v90, s[76:77]
	s_add_u32 s76, s76, s78
	s_addc_u32 s77, s77, 0
	s_add_u32 s76, s76, s78
	s_addc_u32 s77, s77, 0
	global_load_dwordx4 v[140:143], v90, s[82:83]
	s_add_u32 s82, s82, s78
	s_addc_u32 s83, s83, 0
	s_add_u32 s82, s82, s78
	s_addc_u32 s83, s83, 0
	global_load_dwordx4 v[144:147], v90, s[76:77]
	s_add_u32 s76, s76, s78
	s_addc_u32 s77, s77, 0
	s_add_u32 s76, s76, s78
	s_addc_u32 s77, s77, 0
	global_load_dwordx4 v[148:151], v90, s[82:83]
	s_add_u32 s82, s82, s78
	s_addc_u32 s83, s83, 0
	s_add_u32 s82, s82, s78
	s_addc_u32 s83, s83, 0
	global_load_dwordx4 v[152:155], v90, s[76:77]
	s_add_u32 s76, s76, s78
	s_addc_u32 s77, s77, 0
	s_add_u32 s76, s76, s78
	s_addc_u32 s77, s77, 0
	global_load_dwordx4 v[156:159], v90, s[82:83]
	s_add_u32 s82, s82, s78
	s_addc_u32 s83, s83, 0
	s_add_u32 s82, s82, s78
	s_addc_u32 s83, s83, 0
	global_load_dwordx4 v[160:163], v90, s[76:77]
	s_add_u32 s76, s76, s78
	s_addc_u32 s77, s77, 0
	s_add_u32 s76, s76, s78
	s_addc_u32 s77, s77, 0
	global_load_dwordx4 v[164:167], v90, s[82:83]
	s_add_u32 s82, s82, s78
	s_addc_u32 s83, s83, 0
	s_add_u32 s82, s82, s78
	s_addc_u32 s83, s83, 0
	global_load_dwordx4 v[168:171], v90, s[76:77]
	s_add_u32 s76, s76, s78
	s_addc_u32 s77, s77, 0
	s_add_u32 s76, s76, s78
	s_addc_u32 s77, s77, 0
	global_load_dwordx4 v[172:175], v90, s[82:83]
	s_add_u32 s82, s82, s78
	s_addc_u32 s83, s83, 0
	s_add_u32 s82, s82, s78
	s_addc_u32 s83, s83, 0
	global_load_dwordx4 v[176:179], v90, s[76:77]
	s_add_u32 s76, s76, s78
	s_addc_u32 s77, s77, 0
	s_add_u32 s76, s76, s78
	s_addc_u32 s77, s77, 0
	global_load_dwordx4 v[180:183], v90, s[82:83]
	s_add_u32 s82, s82, s78
	s_addc_u32 s83, s83, 0
	s_add_u32 s82, s82, s78
	s_addc_u32 s83, s83, 0
	global_load_dwordx4 v[184:187], v90, s[76:77]
	s_add_u32 s76, s76, s78
	s_addc_u32 s77, s77, 0
	s_add_u32 s76, s76, s78
	s_addc_u32 s77, s77, 0
	global_load_dwordx4 v[188:191], v90, s[82:83]
	s_add_u32 s82, s82, s78
	s_addc_u32 s83, s83, 0
	s_add_u32 s82, s82, s78
	s_addc_u32 s83, s83, 0
	global_load_dwordx4 v[192:195], v90, s[76:77]
	s_add_u32 s76, s76, s78
	s_addc_u32 s77, s77, 0
	s_add_u32 s76, s76, s78
	s_addc_u32 s77, s77, 0
	global_load_dwordx4 v[196:199], v90, s[82:83]
	s_add_u32 s82, s82, s78
	s_addc_u32 s83, s83, 0
	s_add_u32 s82, s82, s78
	s_addc_u32 s83, s83, 0
	global_load_dwordx4 v[200:203], v90, s[76:77]
	s_add_u32 s76, s76, s78
	s_addc_u32 s77, s77, 0
	s_add_u32 s76, s76, s78
	s_addc_u32 s77, s77, 0
	global_load_dwordx4 v[204:207], v90, s[82:83]
	s_add_u32 s82, s82, s78
	s_addc_u32 s83, s83, 0
	s_add_u32 s82, s82, s78
	s_addc_u32 s83, s83, 0
	global_load_dwordx4 v[208:211], v90, s[76:77]
	s_add_u32 s76, s76, s78
	s_addc_u32 s77, s77, 0
	s_add_u32 s76, s76, s78
	s_addc_u32 s77, s77, 0
	global_load_dwordx4 v[212:215], v90, s[82:83]
	s_add_u32 s82, s82, s78
	s_addc_u32 s83, s83, 0
	s_add_u32 s82, s82, s78
	s_addc_u32 s83, s83, 0
	global_load_dwordx4 v[216:219], v90, s[76:77]
	global_load_dwordx4 v[220:223], v90, s[82:83]
	v_lshlrev_b32_e32 v89, 4, v89
	s_mov_b32 s98, 0x0c0c0400
	s_waitcnt vmcnt(29)
	v_max3_f32 v92, |v96|, |v100|, |v104|
	v_max3_f32 v93, |v97|, |v101|, |v105|
	v_max3_f32 v94, |v98|, |v102|, |v106|
	v_max3_f32 v95, |v99|, |v103|, |v107|
	s_waitcnt vmcnt(27)
	v_max3_f32 v92, v92, |v108|, |v112|
	v_max3_f32 v93, v93, |v109|, |v113|
	v_max3_f32 v94, v94, |v110|, |v114|
	v_max3_f32 v95, v95, |v111|, |v115|
	s_waitcnt vmcnt(25)
; __device__ __forceinline__ void convert_i8_strip(const float* W, int ldw, signed char* WT, float* SWp, float* scr, int rmul, int radd) {
;     ...
;         for (int i = 0; i < 64; ++i) am = fmaxf(am, fabsf(v[i]));
;     }
;     scr[kg * 64 + nn] = am;
;     __syncthreads();
;     if (t < 64) { float m = scr[t];
; #pragma unroll
;         for (int k = 1; k < 8; ++k) m = fmaxf(m, scr[k * 64 + t]);
;         scr[512 + t] = m; SWp[rmul * t + radd] = m * (1.f / 127.f); }
;     __syncthreads();
;     const float cm = scr[512 + nn], inv = cm > 0.f ? 127.f / cm : 0.f;
	v_max3_f32 v92, v92, |v116|, |v120|
	v_max3_f32 v93, v93, |v117|, |v121|
	v_max3_f32 v94, v94, |v118|, |v122|
	v_max3_f32 v95, v95, |v119|, |v123|
	s_waitcnt vmcnt(23)
	v_max3_f32 v92, v92, |v124|, |v128|
	v_max3_f32 v93, v93, |v125|, |v129|
	v_max3_f32 v94, v94, |v126|, |v130|
	v_max3_f32 v95, v95, |v127|, |v131|
	s_waitcnt vmcnt(21)
	v_max3_f32 v92, v92, |v132|, |v136|
	v_max3_f32 v93, v93, |v133|, |v137|
	v_max3_f32 v94, v94, |v134|, |v138|
	v_max3_f32 v95, v95, |v135|, |v139|
	s_waitcnt vmcnt(19)
	v_max3_f32 v92, v92, |v140|, |v144|
	v_max3_f32 v93, v93, |v141|, |v145|
	v_max3_f32 v94, v94, |v142|, |v146|
	v_max3_f32 v95, v95, |v143|, |v147|
	s_waitcnt vmcnt(17)
	v_max3_f32 v92, v92, |v148|, |v152|
	v_max3_f32 v93, v93, |v149|, |v153|
	v_max3_f32 v94, v94, |v150|, |v154|
	v_max3_f32 v95, v95, |v151|, |v155|
	s_waitcnt vmcnt(15)
	v_max3_f32 v92, v92, |v156|, |v160|
	v_max3_f32 v93, v93, |v157|, |v161|
	v_max3_f32 v94, v94, |v158|, |v162|
	v_max3_f32 v95, v95, |v159|, |v163|
	s_waitcnt vmcnt(13)
	v_max3_f32 v92, v92, |v164|, |v168|
	v_max3_f32 v93, v93, |v165|, |v169|
	v_max3_f32 v94, v94, |v166|, |v170|
	v_max3_f32 v95, v95, |v167|, |v171|
	s_waitcnt vmcnt(11)
	v_max3_f32 v92, v92, |v172|, |v176|
	v_max3_f32 v93, v93, |v173|, |v177|
	v_max3_f32 v94, v94, |v174|, |v178|
	v_max3_f32 v95, v95, |v175|, |v179|
	s_waitcnt vmcnt(9)
	v_max3_f32 v92, v92, |v180|, |v184|
	v_max3_f32 v93, v93, |v181|, |v185|
	v_max3_f32 v94, v94, |v182|, |v186|
	v_max3_f32 v95, v95, |v183|, |v187|
	s_waitcnt vmcnt(7)
	v_max3_f32 v92, v92, |v188|, |v192|
	v_max3_f32 v93, v93, |v189|, |v193|
	v_max3_f32 v94, v94, |v190|, |v194|
	v_max3_f32 v95, v95, |v191|, |v195|
	s_waitcnt vmcnt(5)
	v_max3_f32 v92, v92, |v196|, |v200|
	v_max3_f32 v93, v93, |v197|, |v201|
	v_max3_f32 v94, v94, |v198|, |v202|
	v_max3_f32 v95, v95, |v199|, |v203|
	s_waitcnt vmcnt(3)
	v_max3_f32 v92, v92, |v204|, |v208|
	v_max3_f32 v93, v93, |v205|, |v209|
	v_max3_f32 v94, v94, |v206|, |v210|
	v_max3_f32 v95, v95, |v207|, |v211|
	s_waitcnt vmcnt(1)
	v_max3_f32 v92, v92, |v212|, |v216|
	v_max3_f32 v93, v93, |v213|, |v217|
	v_max3_f32 v94, v94, |v214|, |v218|
	v_max3_f32 v95, v95, |v215|, |v219|
	s_waitcnt vmcnt(0)
	v_max_f32_e64 v92, v92, |v220|
	v_max_f32_e64 v93, v93, |v221|
	v_max_f32_e64 v94, v94, |v222|
	v_max_f32_e64 v95, v95, |v223|
	ds_write_b128 v88, v[92:95]
	s_waitcnt lgkmcnt(0)
	s_barrier
	ds_read_b128 v[224:227], v89 offset:0
	ds_read_b128 v[228:231], v89 offset:256
	ds_read_b128 v[232:235], v89 offset:512
	ds_read_b128 v[236:239], v89 offset:768
	s_waitcnt lgkmcnt(0)
	v_max3_f32 v92, v224, v228, v232
	v_max_f32_e32 v92, v92, v236
	v_max3_f32 v93, v225, v229, v233
	v_max_f32_e32 v93, v93, v237
	v_max3_f32 v94, v226, v230, v234
	v_max_f32_e32 v94, v94, v238
	v_max3_f32 v95, v227, v231, v235
	v_max_f32_e32 v95, v95, v239
	ds_read_b128 v[224:227], v89 offset:1024
	ds_read_b128 v[228:231], v89 offset:1280
	ds_read_b128 v[232:235], v89 offset:1536
	ds_read_b128 v[236:239], v89 offset:1792
	s_waitcnt lgkmcnt(0)
	v_max3_f32 v92, v92, v224, v228
	v_max3_f32 v92, v92, v232, v236
	v_max3_f32 v93, v93, v225, v229
	v_max3_f32 v93, v93, v233, v237
	v_max3_f32 v94, v94, v226, v230
	v_max3_f32 v94, v94, v234, v238
	v_max3_f32 v95, v95, v227, v231
	v_max3_f32 v95, v95, v235, v239
	ds_read_b128 v[224:227], v89 offset:2048
	ds_read_b128 v[228:231], v89 offset:2304
	ds_read_b128 v[232:235], v89 offset:2560
	ds_read_b128 v[236:239], v89 offset:2816
	s_waitcnt lgkmcnt(0)
	v_max3_f32 v92, v92, v224, v228
	v_max3_f32 v92, v92, v232, v236
	v_max3_f32 v93, v93, v225, v229
	v_max3_f32 v93, v93, v233, v237
	v_max3_f32 v94, v94, v226, v230
	v_max3_f32 v94, v94, v234, v238
	v_max3_f32 v95, v95, v227, v231
	v_max3_f32 v95, v95, v235, v239
	ds_read_b128 v[224:227], v89 offset:3072
	ds_read_b128 v[228:231], v89 offset:3328
	ds_read_b128 v[232:235], v89 offset:3584
	ds_read_b128 v[236:239], v89 offset:3840
	s_waitcnt lgkmcnt(0)
	v_max3_f32 v92, v92, v224, v228
	v_max3_f32 v92, v92, v232, v236
	v_max3_f32 v93, v93, v225, v229
	v_max3_f32 v93, v93, v233, v237
	v_max3_f32 v94, v94, v226, v230
	v_max3_f32 v94, v94, v234, v238
	v_max3_f32 v95, v95, v227, v231
	v_max3_f32 v95, v95, v235, v239
	ds_read_b128 v[224:227], v89 offset:4096
	ds_read_b128 v[228:231], v89 offset:4352
	ds_read_b128 v[232:235], v89 offset:4608
	ds_read_b128 v[236:239], v89 offset:4864
	s_waitcnt lgkmcnt(0)
	v_max3_f32 v92, v92, v224, v228
	v_max3_f32 v92, v92, v232, v236
	v_max3_f32 v93, v93, v225, v229
	v_max3_f32 v93, v93, v233, v237
	v_max3_f32 v94, v94, v226, v230
	v_max3_f32 v94, v94, v234, v238
	v_max3_f32 v95, v95, v227, v231
	v_max3_f32 v95, v95, v235, v239
	ds_read_b128 v[224:227], v89 offset:5120
	ds_read_b128 v[228:231], v89 offset:5376
	ds_read_b128 v[232:235], v89 offset:5632
	ds_read_b128 v[236:239], v89 offset:5888
	s_waitcnt lgkmcnt(0)
	v_max3_f32 v92, v92, v224, v228
	v_max3_f32 v92, v92, v232, v236
	v_max3_f32 v93, v93, v225, v229
	v_max3_f32 v93, v93, v233, v237
	v_max3_f32 v94, v94, v226, v230
	v_max3_f32 v94, v94, v234, v238
	v_max3_f32 v95, v95, v227, v231
	v_max3_f32 v95, v95, v235, v239
	ds_read_b128 v[224:227], v89 offset:6144
	ds_read_b128 v[228:231], v89 offset:6400
	ds_read_b128 v[232:235], v89 offset:6656
	ds_read_b128 v[236:239], v89 offset:6912
	s_waitcnt lgkmcnt(0)
	v_max3_f32 v92, v92, v224, v228
	v_max3_f32 v92, v92, v232, v236
	v_max3_f32 v93, v93, v225, v229
	v_max3_f32 v93, v93, v233, v237
	v_max3_f32 v94, v94, v226, v230
	v_max3_f32 v94, v94, v234, v238
	v_max3_f32 v95, v95, v227, v231
	v_max3_f32 v95, v95, v235, v239
	ds_read_b128 v[224:227], v89 offset:7168
	ds_read_b128 v[228:231], v89 offset:7424
	ds_read_b128 v[232:235], v89 offset:7680
	ds_read_b128 v[236:239], v89 offset:7936
	s_waitcnt lgkmcnt(0)
	v_max3_f32 v92, v92, v224, v228
	v_max3_f32 v92, v92, v232, v236
	v_max3_f32 v93, v93, v225, v229
	v_max3_f32 v93, v93, v233, v237
	v_max3_f32 v94, v94, v226, v230
	v_max3_f32 v94, v94, v234, v238
	v_max3_f32 v95, v95, v227, v231
	v_max3_f32 v95, v95, v235, v239
	s_barrier
; __device__ __forceinline__ void convert_i8_strip(const float* W, int ldw, signed char* WT, float* SWp, float* scr, int rmul, int radd) {
;     ...
;     if (t < 64) { float m = scr[t];
; #pragma unroll
;         for (int k = 1; k < 8; ++k) m = fmaxf(m, scr[k * 64 + t]);
;         scr[512 + t] = m; SWp[rmul * t + radd] = m * (1.f / 127.f); }
;     __syncthreads();
;     const float cm = scr[512 + nn], inv = cm > 0.f ? 127.f / cm : 0.f;
;     __syncthreads();
;     float r[8];
; #pragma unroll
;     for (int i = 0; i < 8; ++i) r[i] = W[(size_t)(kg + 8 * i) * ldw + nn];
; #pragma unroll 1
;     for (int kb = 0; kb < 16; ++kb) {
; #pragma unroll
;         for (int i = 0; i < 8; ++i) scr[1024 + (kg + 8 * i) * 65 + nn] = r[i] * inv + 12582912.0f;
;         __syncthreads();
;         if (kb + 1 < 16) {
; #pragma unroll
;             for (int i = 0; i < 8; ++i) r[i] = W[(size_t)((kb + 1) * 64 + kg + 8 * i) * ldw + nn]; }
;         { const int on = t >> 3, kc = t & 7;
;           const unsigned* sp = (const unsigned*)(scr + 1024 + (8 * kc) * 65 + on);
;           u32x2 o; o.x = (sp[0] & 0xffu) | ((sp[65] & 0xffu) << 8) | ((sp[2 * 65] & 0xffu) << 16) | (sp[3 * 65] << 24);
;           o.y = (sp[4 * 65] & 0xffu) | ((sp[5 * 65] & 0xffu) << 8) | ((sp[6 * 65] & 0xffu) << 16) | (sp[7 * 65] << 24);
;           *(u32x2*)(WT + (ptrdiff_t)(rmul * on + radd) * DM + kb * 64 + 8 * kc) = o; }
	s_mov_b32 s99, 0x42fe0000
	s_add_u32 s74, s81, 4
	v_lshrrev_b32_e32 v252, 4, v89
	v_lshlrev_b32_e32 v252, s74, v252
	v_cmp_gt_u32_e32 vcc, 16, v0
	s_and_saveexec_b64 s[100:101], vcc
	v_mul_f32_e32 v224, 0x3c010204, v92
	v_mul_f32_e32 v225, 0x3c010204, v93
	v_mul_f32_e32 v226, 0x3c010204, v94
	v_mul_f32_e32 v227, 0x3c010204, v95
	s_lshl_b32 s75, 0, s81
	v_add_u32_e32 v253, s75, v252
	global_store_dword v253, v224, s[72:73]
	s_lshl_b32 s75, 4, s81
	v_add_u32_e32 v253, s75, v252
	global_store_dword v253, v225, s[72:73]
	s_lshl_b32 s75, 8, s81
	v_add_u32_e32 v253, s75, v252
	global_store_dword v253, v226, s[72:73]
	s_lshl_b32 s75, 12, s81
	v_add_u32_e32 v253, s75, v252
	global_store_dword v253, v227, s[72:73]
	s_mov_b64 exec, s[100:101]
	v_div_scale_f32 v244, s[74:75], v92, v92, s99
	v_rcp_f32_e32 v245, v244
	s_nop 0
	v_fma_f32 v246, -v244, v245, 1.0
	v_fmac_f32_e32 v245, v246, v245
	v_div_scale_f32 v246, vcc, s99, v92, s99
	v_mul_f32_e32 v247, v246, v245
	v_fma_f32 v252, -v244, v247, v246
	v_fmac_f32_e32 v247, v252, v245
	v_fma_f32 v244, -v244, v247, v246
	s_nop 0
	v_div_fmas_f32 v244, v244, v245, v247
	v_div_fixup_f32 v244, v244, v92, s99
	v_cmp_lt_f32_e32 vcc, 0, v92
	s_nop 1
	v_cndmask_b32_e32 v240, 0, v244, vcc
	v_div_scale_f32 v244, s[74:75], v93, v93, s99
	v_rcp_f32_e32 v245, v244
	s_nop 0
	v_fma_f32 v246, -v244, v245, 1.0
	v_fmac_f32_e32 v245, v246, v245
	v_div_scale_f32 v246, vcc, s99, v93, s99
	v_mul_f32_e32 v247, v246, v245
	v_fma_f32 v252, -v244, v247, v246
	v_fmac_f32_e32 v247, v252, v245
	v_fma_f32 v244, -v244, v247, v246
	s_nop 0
	v_div_fmas_f32 v244, v244, v245, v247
	v_div_fixup_f32 v244, v244, v93, s99
	v_cmp_lt_f32_e32 vcc, 0, v93
	s_nop 1
	v_cndmask_b32_e32 v241, 0, v244, vcc
	v_div_scale_f32 v244, s[74:75], v94, v94, s99
	v_rcp_f32_e32 v245, v244
	s_nop 0
	v_fma_f32 v246, -v244, v245, 1.0
	v_fmac_f32_e32 v245, v246, v245
	v_div_scale_f32 v246, vcc, s99, v94, s99
	v_mul_f32_e32 v247, v246, v245
	v_fma_f32 v252, -v244, v247, v246
	v_fmac_f32_e32 v247, v252, v245
	v_fma_f32 v244, -v244, v247, v246
	s_nop 0
	v_div_fmas_f32 v244, v244, v245, v247
	v_div_fixup_f32 v244, v244, v94, s99
	v_cmp_lt_f32_e32 vcc, 0, v94
	s_nop 1
	v_cndmask_b32_e32 v242, 0, v244, vcc
	v_div_scale_f32 v244, s[74:75], v95, v95, s99
	v_rcp_f32_e32 v245, v244
	s_nop 0
	v_fma_f32 v246, -v244, v245, 1.0
	v_fmac_f32_e32 v245, v246, v245
	v_div_scale_f32 v246, vcc, s99, v95, s99
	v_mul_f32_e32 v247, v246, v245
	v_fma_f32 v252, -v244, v247, v246
	v_fmac_f32_e32 v247, v252, v245
	v_fma_f32 v244, -v244, v247, v246
	s_nop 0
	v_div_fmas_f32 v244, v244, v245, v247
	v_div_fixup_f32 v244, v244, v95, s99
	v_cmp_lt_f32_e32 vcc, 0, v95
	s_nop 1
	v_cndmask_b32_e32 v243, 0, v244, vcc
	v_fmaak_f32 v96, v240, v96, 0x4b400000
	v_fmaak_f32 v100, v240, v100, 0x4b400000
	v_fmaak_f32 v104, v240, v104, 0x4b400000
	v_fmaak_f32 v108, v240, v108, 0x4b400000
	v_perm_b32 v252, v100, v96, s98
	v_perm_b32 v253, v108, v104, s98
	v_lshl_or_b32 v224, v253, 16, v252
	v_fmaak_f32 v112, v240, v112, 0x4b400000
	v_fmaak_f32 v116, v240, v116, 0x4b400000
	v_fmaak_f32 v120, v240, v120, 0x4b400000
	v_fmaak_f32 v124, v240, v124, 0x4b400000
	v_perm_b32 v252, v116, v112, s98
	v_perm_b32 v253, v124, v120, s98
	v_lshl_or_b32 v225, v253, 16, v252
	v_fmaak_f32 v128, v240, v128, 0x4b400000
	v_fmaak_f32 v132, v240, v132, 0x4b400000
	v_fmaak_f32 v136, v240, v136, 0x4b400000
	v_fmaak_f32 v140, v240, v140, 0x4b400000
	v_perm_b32 v252, v132, v128, s98
	v_perm_b32 v253, v140, v136, s98
	v_lshl_or_b32 v226, v253, 16, v252
	v_fmaak_f32 v144, v240, v144, 0x4b400000
	v_fmaak_f32 v148, v240, v148, 0x4b400000
	v_fmaak_f32 v152, v240, v152, 0x4b400000
	v_fmaak_f32 v156, v240, v156, 0x4b400000
	v_perm_b32 v252, v148, v144, s98
	v_perm_b32 v253, v156, v152, s98
	v_lshl_or_b32 v227, v253, 16, v252
	global_store_dwordx4 v248, v[224:227], s[70:71] offset:0
	v_fmaak_f32 v97, v241, v97, 0x4b400000
	v_fmaak_f32 v101, v241, v101, 0x4b400000
	v_fmaak_f32 v105, v241, v105, 0x4b400000
	v_fmaak_f32 v109, v241, v109, 0x4b400000
	v_perm_b32 v252, v101, v97, s98
	v_perm_b32 v253, v109, v105, s98
	v_lshl_or_b32 v228, v253, 16, v252
	v_fmaak_f32 v113, v241, v113, 0x4b400000
	v_fmaak_f32 v117, v241, v117, 0x4b400000
	v_fmaak_f32 v121, v241, v121, 0x4b400000
	v_fmaak_f32 v125, v241, v125, 0x4b400000
	v_perm_b32 v252, v117, v113, s98
	v_perm_b32 v253, v125, v121, s98
	v_lshl_or_b32 v229, v253, 16, v252
	v_fmaak_f32 v129, v241, v129, 0x4b400000
	v_fmaak_f32 v133, v241, v133, 0x4b400000
	v_fmaak_f32 v137, v241, v137, 0x4b400000
	v_fmaak_f32 v141, v241, v141, 0x4b400000
	v_perm_b32 v252, v133, v129, s98
	v_perm_b32 v253, v141, v137, s98
	v_lshl_or_b32 v230, v253, 16, v252
	v_fmaak_f32 v145, v241, v145, 0x4b400000
	v_fmaak_f32 v149, v241, v149, 0x4b400000
	v_fmaak_f32 v153, v241, v153, 0x4b400000
	v_fmaak_f32 v157, v241, v157, 0x4b400000
	v_perm_b32 v252, v149, v145, s98
	v_perm_b32 v253, v157, v153, s98
	v_lshl_or_b32 v231, v253, 16, v252
	global_store_dwordx4 v249, v[228:231], s[70:71] offset:0
	v_fmaak_f32 v98, v242, v98, 0x4b400000
	v_fmaak_f32 v102, v242, v102, 0x4b400000
	v_fmaak_f32 v106, v242, v106, 0x4b400000
	v_fmaak_f32 v110, v242, v110, 0x4b400000
	v_perm_b32 v252, v102, v98, s98
	v_perm_b32 v253, v110, v106, s98
	v_lshl_or_b32 v232, v253, 16, v252
	v_fmaak_f32 v114, v242, v114, 0x4b400000
	v_fmaak_f32 v118, v242, v118, 0x4b400000
	v_fmaak_f32 v122, v242, v122, 0x4b400000
	v_fmaak_f32 v126, v242, v126, 0x4b400000
	v_perm_b32 v252, v118, v114, s98
	v_perm_b32 v253, v126, v122, s98
	v_lshl_or_b32 v233, v253, 16, v252
	v_fmaak_f32 v130, v242, v130, 0x4b400000
	v_fmaak_f32 v134, v242, v134, 0x4b400000
	v_fmaak_f32 v138, v242, v138, 0x4b400000
; __device__ __forceinline__ void convert_i8_strip(const float* W, int ldw, signed char* WT, float* SWp, float* scr, int rmul, int radd) {
;     ...
;     for (int kb = 0; kb < 16; ++kb) {
; #pragma unroll
;         for (int i = 0; i < 8; ++i) scr[1024 + (kg + 8 * i) * 65 + nn] = r[i] * inv + 12582912.0f;
;         __syncthreads();
;         if (kb + 1 < 16) {
; #pragma unroll
;             for (int i = 0; i < 8; ++i) r[i] = W[(size_t)((kb + 1) * 64 + kg + 8 * i) * ldw + nn]; }
;         { const int on = t >> 3, kc = t & 7;
;           const unsigned* sp = (const unsigned*)(scr + 1024 + (8 * kc) * 65 + on);
;           u32x2 o; o.x = (sp[0] & 0xffu) | ((sp[65] & 0xffu) << 8) | ((sp[2 * 65] & 0xffu) << 16) | (sp[3 * 65] << 24);
;           o.y = (sp[4 * 65] & 0xffu) | ((sp[5 * 65] & 0xffu) << 8) | ((sp[6 * 65] & 0xffu) << 16) | (sp[7 * 65] << 24);
;           *(u32x2*)(WT + (ptrdiff_t)(rmul * on + radd) * DM + kb * 64 + 8 * kc) = o; }
;         __syncthreads();
	v_fmaak_f32 v142, v242, v142, 0x4b400000
	v_perm_b32 v252, v134, v130, s98
	v_perm_b32 v253, v142, v138, s98
	v_lshl_or_b32 v234, v253, 16, v252
	v_fmaak_f32 v146, v242, v146, 0x4b400000
	v_fmaak_f32 v150, v242, v150, 0x4b400000
	v_fmaak_f32 v154, v242, v154, 0x4b400000
	v_fmaak_f32 v158, v242, v158, 0x4b400000
	v_perm_b32 v252, v150, v146, s98
	v_perm_b32 v253, v158, v154, s98
	v_lshl_or_b32 v235, v253, 16, v252
	global_store_dwordx4 v250, v[232:235], s[70:71] offset:0
	v_fmaak_f32 v99, v243, v99, 0x4b400000
	v_fmaak_f32 v103, v243, v103, 0x4b400000
	v_fmaak_f32 v107, v243, v107, 0x4b400000
	v_fmaak_f32 v111, v243, v111, 0x4b400000
	v_perm_b32 v252, v103, v99, s98
	v_perm_b32 v253, v111, v107, s98
	v_lshl_or_b32 v236, v253, 16, v252
	v_fmaak_f32 v115, v243, v115, 0x4b400000
	v_fmaak_f32 v119, v243, v119, 0x4b400000
	v_fmaak_f32 v123, v243, v123, 0x4b400000
	v_fmaak_f32 v127, v243, v127, 0x4b400000
	v_perm_b32 v252, v119, v115, s98
	v_perm_b32 v253, v127, v123, s98
	v_lshl_or_b32 v237, v253, 16, v252
	v_fmaak_f32 v131, v243, v131, 0x4b400000
	v_fmaak_f32 v135, v243, v135, 0x4b400000
	v_fmaak_f32 v139, v243, v139, 0x4b400000
	v_fmaak_f32 v143, v243, v143, 0x4b400000
	v_perm_b32 v252, v135, v131, s98
	v_perm_b32 v253, v143, v139, s98
	v_lshl_or_b32 v238, v253, 16, v252
	v_fmaak_f32 v147, v243, v147, 0x4b400000
	v_fmaak_f32 v151, v243, v151, 0x4b400000
	v_fmaak_f32 v155, v243, v155, 0x4b400000
	v_fmaak_f32 v159, v243, v159, 0x4b400000
	v_perm_b32 v252, v151, v147, s98
	v_perm_b32 v253, v159, v155, s98
	v_lshl_or_b32 v239, v253, 16, v252
	global_store_dwordx4 v251, v[236:239], s[70:71] offset:0
	s_nop 1
	v_fmaak_f32 v160, v240, v160, 0x4b400000
	v_fmaak_f32 v164, v240, v164, 0x4b400000
	v_fmaak_f32 v168, v240, v168, 0x4b400000
	v_fmaak_f32 v172, v240, v172, 0x4b400000
	v_perm_b32 v252, v164, v160, s98
	v_perm_b32 v253, v172, v168, s98
	v_lshl_or_b32 v224, v253, 16, v252
	v_fmaak_f32 v176, v240, v176, 0x4b400000
	v_fmaak_f32 v180, v240, v180, 0x4b400000
	v_fmaak_f32 v184, v240, v184, 0x4b400000
	v_fmaak_f32 v188, v240, v188, 0x4b400000
	v_perm_b32 v252, v180, v176, s98
	v_perm_b32 v253, v188, v184, s98
	v_lshl_or_b32 v225, v253, 16, v252
	v_fmaak_f32 v192, v240, v192, 0x4b400000
	v_fmaak_f32 v196, v240, v196, 0x4b400000
	v_fmaak_f32 v200, v240, v200, 0x4b400000
	v_fmaak_f32 v204, v240, v204, 0x4b400000
	v_perm_b32 v252, v196, v192, s98
	v_perm_b32 v253, v204, v200, s98
	v_lshl_or_b32 v226, v253, 16, v252
	v_fmaak_f32 v208, v240, v208, 0x4b400000
	v_fmaak_f32 v212, v240, v212, 0x4b400000
	v_fmaak_f32 v216, v240, v216, 0x4b400000
	v_fmaak_f32 v220, v240, v220, 0x4b400000
	v_perm_b32 v252, v212, v208, s98
	v_perm_b32 v253, v220, v216, s98
	v_lshl_or_b32 v227, v253, 16, v252
	global_store_dwordx4 v248, v[224:227], s[70:71] offset:16
	v_fmaak_f32 v161, v241, v161, 0x4b400000
	v_fmaak_f32 v165, v241, v165, 0x4b400000
	v_fmaak_f32 v169, v241, v169, 0x4b400000
	v_fmaak_f32 v173, v241, v173, 0x4b400000
	v_perm_b32 v252, v165, v161, s98
	v_perm_b32 v253, v173, v169, s98
	v_lshl_or_b32 v228, v253, 16, v252
	v_fmaak_f32 v177, v241, v177, 0x4b400000
	v_fmaak_f32 v181, v241, v181, 0x4b400000
	v_fmaak_f32 v185, v241, v185, 0x4b400000
	v_fmaak_f32 v189, v241, v189, 0x4b400000
	v_perm_b32 v252, v181, v177, s98
	v_perm_b32 v253, v189, v185, s98
	v_lshl_or_b32 v229, v253, 16, v252
	v_fmaak_f32 v193, v241, v193, 0x4b400000
	v_fmaak_f32 v197, v241, v197, 0x4b400000
	v_fmaak_f32 v201, v241, v201, 0x4b400000
	v_fmaak_f32 v205, v241, v205, 0x4b400000
	v_perm_b32 v252, v197, v193, s98
	v_perm_b32 v253, v205, v201, s98
	v_lshl_or_b32 v230, v253, 16, v252
	v_fmaak_f32 v209, v241, v209, 0x4b400000
	v_fmaak_f32 v213, v241, v213, 0x4b400000
	v_fmaak_f32 v217, v241, v217, 0x4b400000
	v_fmaak_f32 v221, v241, v221, 0x4b400000
	v_perm_b32 v252, v213, v209, s98
	v_perm_b32 v253, v221, v217, s98
	v_lshl_or_b32 v231, v253, 16, v252
	global_store_dwordx4 v249, v[228:231], s[70:71] offset:16
	v_fmaak_f32 v162, v242, v162, 0x4b400000
	v_fmaak_f32 v166, v242, v166, 0x4b400000
	v_fmaak_f32 v170, v242, v170, 0x4b400000
	v_fmaak_f32 v174, v242, v174, 0x4b400000
	v_perm_b32 v252, v166, v162, s98
	v_perm_b32 v253, v174, v170, s98
	v_lshl_or_b32 v232, v253, 16, v252
	v_fmaak_f32 v178, v242, v178, 0x4b400000
	v_fmaak_f32 v182, v242, v182, 0x4b400000
	v_fmaak_f32 v186, v242, v186, 0x4b400000
	v_fmaak_f32 v190, v242, v190, 0x4b400000
	v_perm_b32 v252, v182, v178, s98
	v_perm_b32 v253, v190, v186, s98
	v_lshl_or_b32 v233, v253, 16, v252
	v_fmaak_f32 v194, v242, v194, 0x4b400000
	v_fmaak_f32 v198, v242, v198, 0x4b400000
	v_fmaak_f32 v202, v242, v202, 0x4b400000
	v_fmaak_f32 v206, v242, v206, 0x4b400000
	v_perm_b32 v252, v198, v194, s98
	v_perm_b32 v253, v206, v202, s98
	v_lshl_or_b32 v234, v253, 16, v252
	v_fmaak_f32 v210, v242, v210, 0x4b400000
	v_fmaak_f32 v214, v242, v214, 0x4b400000
	v_fmaak_f32 v218, v242, v218, 0x4b400000
	v_fmaak_f32 v222, v242, v222, 0x4b400000
	v_perm_b32 v252, v214, v210, s98
	v_perm_b32 v253, v222, v218, s98
	v_lshl_or_b32 v235, v253, 16, v252
	global_store_dwordx4 v250, v[232:235], s[70:71] offset:16
	v_fmaak_f32 v163, v243, v163, 0x4b400000
	v_fmaak_f32 v167, v243, v167, 0x4b400000
	v_fmaak_f32 v171, v243, v171, 0x4b400000
	v_fmaak_f32 v175, v243, v175, 0x4b400000
	v_perm_b32 v252, v167, v163, s98
	v_perm_b32 v253, v175, v171, s98
	v_lshl_or_b32 v236, v253, 16, v252
	v_fmaak_f32 v179, v243, v179, 0x4b400000
	v_fmaak_f32 v183, v243, v183, 0x4b400000
	v_fmaak_f32 v187, v243, v187, 0x4b400000
	v_fmaak_f32 v191, v243, v191, 0x4b400000
	v_perm_b32 v252, v183, v179, s98
	v_perm_b32 v253, v191, v187, s98
	v_lshl_or_b32 v237, v253, 16, v252
	v_fmaak_f32 v195, v243, v195, 0x4b400000
	v_fmaak_f32 v199, v243, v199, 0x4b400000
	v_fmaak_f32 v203, v243, v203, 0x4b400000
	v_fmaak_f32 v207, v243, v207, 0x4b400000
	v_perm_b32 v252, v199, v195, s98
	v_perm_b32 v253, v207, v203, s98
	v_lshl_or_b32 v238, v253, 16, v252
	v_fmaak_f32 v211, v243, v211, 0x4b400000
	v_fmaak_f32 v215, v243, v215, 0x4b400000
	v_fmaak_f32 v219, v243, v219, 0x4b400000
	v_fmaak_f32 v223, v243, v223, 0x4b400000
	v_perm_b32 v252, v215, v211, s98
	v_perm_b32 v253, v223, v219, s98
	v_lshl_or_b32 v239, v253, 16, v252
	global_store_dwordx4 v251, v[236:239], s[70:71] offset:16
	s_branch .LBB0_1584
	s_nop 0
	s_nop 0
	s_nop 0
	s_nop 0
	s_nop 0
	s_nop 0
	s_nop 0
	s_nop 0
	s_nop 0
	s_nop 0
	s_nop 0
	s_nop 0
	s_nop 0
	s_nop 0
	s_nop 0
	s_nop 0
	s_nop 0
	s_nop 0
	s_nop 0
	s_nop 0
	s_nop 0
	s_nop 0
	s_nop 0
	s_nop 0
	s_nop 0
	s_nop 0
	s_nop 0
	s_nop 0
	s_nop 0
	s_nop 0
	s_nop 0
	s_nop 0
	s_nop 0
	s_nop 0
	s_nop 0
	s_nop 0
	s_nop 0
	s_nop 0
	s_nop 0
	s_nop 0
	s_nop 0
	s_nop 0
	s_nop 0
	s_nop 0
	s_nop 0
	s_nop 0
	s_nop 0
	s_nop 0
	s_nop 0
	s_nop 0
	s_nop 0
	s_nop 0
	s_nop 0
	s_nop 0
	s_nop 0
	s_nop 0
	s_nop 0
	s_nop 0
	s_nop 0
	s_nop 0

; __global__ void __launch_bounds__(NTHREADS, 2) fwd_kernel(Args a) {
;     extern __shared__ __attribute__((aligned(16))) unsigned char lds_raw[];
;     const int lo = a.ph_lo, hi = a.ph_hi;
	.amdhsa_kernel _Z10fwd_kernel4Args
		.amdhsa_group_segment_fixed_size 0
		.amdhsa_private_segment_fixed_size 0
		.amdhsa_kernarg_size 408
		.amdhsa_user_sgpr_count 2
		.amdhsa_user_sgpr_dispatch_ptr 0
		.amdhsa_user_sgpr_queue_ptr 0
		.amdhsa_user_sgpr_kernarg_segment_ptr 1
		.amdhsa_user_sgpr_dispatch_id 0
		.amdhsa_user_sgpr_kernarg_preload_length 0
		.amdhsa_user_sgpr_kernarg_preload_offset 0
		.amdhsa_user_sgpr_private_segment_size 0
		.amdhsa_uses_dynamic_stack 0
		.amdhsa_enable_private_segment 0
		.amdhsa_system_sgpr_workgroup_id_x 1
		.amdhsa_system_sgpr_workgroup_id_y 0
		.amdhsa_system_sgpr_workgroup_id_z 0
		.amdhsa_system_sgpr_workgroup_info 0
		.amdhsa_system_vgpr_workitem_id 0
		.amdhsa_next_free_vgpr 256
		.amdhsa_next_free_sgpr 102
		.amdhsa_accum_offset 256
		.amdhsa_reserve_vcc 1
		.amdhsa_float_round_mode_32 0
		.amdhsa_float_round_mode_16_64 0
		.amdhsa_float_denorm_mode_32 3
		.amdhsa_float_denorm_mode_16_64 3
		.amdhsa_dx10_clamp 1
		.amdhsa_ieee_mode 1
		.amdhsa_fp16_overflow 0
		.amdhsa_tg_split 0
		.amdhsa_exception_fp_ieee_invalid_op 0
		.amdhsa_exception_fp_denorm_src 0
		.amdhsa_exception_fp_ieee_div_zero 0
		.amdhsa_exception_fp_ieee_overflow 0
		.amdhsa_exception_fp_ieee_underflow 0
		.amdhsa_exception_fp_ieee_inexact 0
		.amdhsa_exception_int_div_zero 0
	.end_amdhsa_kernel

; __global__ void __launch_bounds__(NTHREADS, 2) fwd_kernel(Args a) {
;     extern __shared__ __attribute__((aligned(16))) unsigned char lds_raw[];
;     const int lo = a.ph_lo, hi = a.ph_hi;
amdhsa.kernels:
  - .agpr_count:     0
    .args:
      - .offset:         0
        .size:           152
        .value_kind:     by_value
      - .offset:         152
        .size:           4
        .value_kind:     hidden_block_count_x
      - .offset:         156
        .size:           4
        .value_kind:     hidden_block_count_y
      - .offset:         160
        .size:           4
        .value_kind:     hidden_block_count_z
      - .offset:         164
        .size:           2
        .value_kind:     hidden_group_size_x
      - .offset:         166
        .size:           2
        .value_kind:     hidden_group_size_y
      - .offset:         168
        .size:           2
        .value_kind:     hidden_group_size_z
      - .offset:         170
        .size:           2
        .value_kind:     hidden_remainder_x
      - .offset:         172
        .size:           2
        .value_kind:     hidden_remainder_y
      - .offset:         174
        .size:           2
        .value_kind:     hidden_remainder_z
      - .offset:         192
        .size:           8
        .value_kind:     hidden_global_offset_x
      - .offset:         200
        .size:           8
        .value_kind:     hidden_global_offset_y
      - .offset:         208
        .size:           8
        .value_kind:     hidden_global_offset_z
      - .offset:         216
        .size:           2
        .value_kind:     hidden_grid_dims
      - .offset:         272
        .size:           4
        .value_kind:     hidden_dynamic_lds_size
    .group_segment_fixed_size: 0
    .kernarg_segment_align: 8
    .kernarg_segment_size: 408
    .language:       OpenCL C
    .language_version:
      - 2
      - 0
    .max_flat_workgroup_size: 512
    .name:           _Z10fwd_kernel4Args
    .private_segment_fixed_size: 0
    .sgpr_count:     108
    .sgpr_spill_count: 44
    .symbol:         _Z10fwd_kernel4Args.kd
    .uniform_work_group_size: 1
    .uses_dynamic_stack: false
    .vgpr_count:     256
    .vgpr_spill_count: 0
    .wavefront_size: 64
